# strategy 9 loop-edge edit: K-loop counter/pointer updates and exit compare moved in front of the loop-back barrier in all seven GEMM loops
# baseline (speedup 1.0000x reference)
.LBB0_122:
	ds_read_b128 v[154:157], v151
	ds_read_b128 v[158:161], v151 offset:1024
	ds_read_b128 v[162:165], v151 offset:2048
	ds_read_b128 v[166:169], v151 offset:3072
	ds_read_b128 v[170:173], v152
	ds_read_b128 v[174:177], v152 offset:1024
	ds_read_b128 v[178:181], v152 offset:2048
	ds_read_b128 v[182:185], v152 offset:3072
	s_add_u32 s30, s28, 0xfff80080
	s_addc_u32 s31, s29, -1
	s_cmp_eq_u32 s91, 28
	s_cselect_b32 s47, s21, s31
	s_cselect_b32 s46, s87, s30
	s_cselect_b32 s31, s19, s90
	s_cselect_b32 s30, s88, s89
	v_lshl_add_u64 v[218:219], s[28:29], 0, v[138:139]
	s_add_i32 m0, s27, 0xc000
	ds_read_b128 v[186:189], v153
	ds_read_b128 v[190:193], v153 offset:1024
	ds_read_b128 v[194:197], v153 offset:2048
	ds_read_b128 v[198:201], v153 offset:3072
	ds_read_b128 v[202:205], v153 offset:4096
	ds_read_b128 v[206:209], v153 offset:5120
	ds_read_b128 v[210:213], v153 offset:6144
	ds_read_b128 v[214:217], v153 offset:7168
	global_load_lds_dwordx4 v[218:219], off
	v_lshl_add_u64 v[218:219], s[28:29], 0, v[140:141]
	s_add_i32 m0, s27, 0xe000
	s_nop 0
	global_load_lds_dwordx4 v[218:219], off
	s_waitcnt vmcnt(8)
	s_waitcnt lgkmcnt(0)
	s_barrier
	s_setprio 1
	s_waitcnt lgkmcnt(0)
	v_mfma_f32_16x16x32_bf16 v[126:129], v[154:157], v[186:189], v[126:129]
	v_mfma_f32_16x16x32_bf16 v[122:125], v[162:165], v[186:189], v[122:125]
	v_mfma_f32_16x16x32_bf16 v[118:121], v[154:157], v[194:197], v[118:121]
	v_mfma_f32_16x16x32_bf16 v[114:117], v[162:165], v[194:197], v[114:117]
	v_mfma_f32_16x16x32_bf16 v[102:105], v[154:157], v[202:205], v[102:105]
	v_mfma_f32_16x16x32_bf16 v[98:101], v[162:165], v[202:205], v[98:101]
	v_mfma_f32_16x16x32_bf16 v[86:89], v[154:157], v[210:213], v[86:89]
	v_mfma_f32_16x16x32_bf16 v[78:81], v[162:165], v[210:213], v[78:81]
	v_mfma_f32_16x16x32_bf16 v[126:129], v[158:161], v[190:193], v[126:129]
	v_mfma_f32_16x16x32_bf16 v[122:125], v[166:169], v[190:193], v[122:125]
	v_mfma_f32_16x16x32_bf16 v[118:121], v[158:161], v[198:201], v[118:121]
	v_mfma_f32_16x16x32_bf16 v[114:117], v[166:169], v[198:201], v[114:117]
	v_mfma_f32_16x16x32_bf16 v[102:105], v[158:161], v[206:209], v[102:105]
	v_mfma_f32_16x16x32_bf16 v[98:101], v[166:169], v[206:209], v[98:101]
	v_mfma_f32_16x16x32_bf16 v[86:89], v[158:161], v[214:217], v[86:89]
	v_mfma_f32_16x16x32_bf16 v[78:81], v[166:169], v[214:217], v[78:81]
	s_setprio 0
	s_setprio 1
	v_mfma_f32_16x16x32_bf16 v[110:113], v[170:173], v[186:189], v[110:113]
	v_mfma_f32_16x16x32_bf16 v[106:109], v[178:181], v[186:189], v[106:109]
	v_mfma_f32_16x16x32_bf16 v[94:97], v[170:173], v[194:197], v[94:97]
	v_mfma_f32_16x16x32_bf16 v[90:93], v[178:181], v[194:197], v[90:93]
	v_mfma_f32_16x16x32_bf16 v[82:85], v[170:173], v[202:205], v[82:85]
	v_mfma_f32_16x16x32_bf16 v[74:77], v[178:181], v[202:205], v[74:77]
	v_mfma_f32_16x16x32_bf16 v[70:73], v[170:173], v[210:213], v[70:73]
	v_mfma_f32_16x16x32_bf16 v[66:69], v[178:181], v[210:213], v[66:69]
	v_mfma_f32_16x16x32_bf16 v[110:113], v[174:177], v[190:193], v[110:113]
	v_mfma_f32_16x16x32_bf16 v[106:109], v[182:185], v[190:193], v[106:109]
	v_mfma_f32_16x16x32_bf16 v[94:97], v[174:177], v[198:201], v[94:97]
	v_mfma_f32_16x16x32_bf16 v[90:93], v[182:185], v[198:201], v[90:93]
	v_mfma_f32_16x16x32_bf16 v[82:85], v[174:177], v[206:209], v[82:85]
	v_mfma_f32_16x16x32_bf16 v[74:77], v[182:185], v[206:209], v[74:77]
	v_mfma_f32_16x16x32_bf16 v[70:73], v[174:177], v[214:217], v[70:73]
	v_mfma_f32_16x16x32_bf16 v[66:69], v[182:185], v[214:217], v[66:69]
	s_setprio 0
	s_barrier
	s_add_i32 s92, s73, s53
	v_lshl_add_u64 v[218:219], s[30:31], 0, v[134:135]
	s_mov_b32 m0, s92
	ds_read_b128 v[186:189], v153 offset:16384
	ds_read_b128 v[190:193], v153 offset:17408
	ds_read_b128 v[194:197], v153 offset:18432
	ds_read_b128 v[198:201], v153 offset:19456
	ds_read_b128 v[202:205], v153 offset:20480
	ds_read_b128 v[206:209], v153 offset:21504
	ds_read_b128 v[210:213], v153 offset:22528
	ds_read_b128 v[214:217], v153 offset:23552
	global_load_lds_dwordx4 v[218:219], off
	s_add_i32 m0, s92, 0x2000
	s_add_u32 s92, s30, 0x80000
	v_lshl_add_u64 v[220:221], s[30:31], 0, v[130:131]
	s_addc_u32 s93, s31, 0
	s_add_i32 s94, s83, s53
	global_load_lds_dwordx4 v[220:221], off
	v_lshl_add_u64 v[222:223], s[92:93], 0, v[134:135]
	s_mov_b32 m0, s94
	v_lshl_add_u64 v[224:225], s[46:47], 0, v[132:133]
	global_load_lds_dwordx4 v[222:223], off
	v_lshl_add_u64 v[222:223], s[92:93], 0, v[130:131]
	s_add_i32 m0, s94, 0x2000
	s_nop 0
	global_load_lds_dwordx4 v[222:223], off
	v_lshl_add_u64 v[222:223], s[46:47], 0, v[136:137]
	s_mov_b32 m0, s27
	s_nop 0
	global_load_lds_dwordx4 v[222:223], off
	s_mov_b32 m0, s76
	s_nop 0
	global_load_lds_dwordx4 v[224:225], off
	s_waitcnt vmcnt(8)
	s_waitcnt lgkmcnt(0)
	s_barrier
	s_setprio 1
	s_waitcnt lgkmcnt(0)
	v_mfma_f32_16x16x32_bf16 v[62:65], v[154:157], v[186:189], v[62:65]
	v_mfma_f32_16x16x32_bf16 v[58:61], v[162:165], v[186:189], v[58:61]
	v_mfma_f32_16x16x32_bf16 v[54:57], v[154:157], v[194:197], v[54:57]
	v_mfma_f32_16x16x32_bf16 v[46:49], v[162:165], v[194:197], v[46:49]
	v_mfma_f32_16x16x32_bf16 v[38:41], v[154:157], v[202:205], v[38:41]
	v_mfma_f32_16x16x32_bf16 v[30:33], v[162:165], v[202:205], v[30:33]
	v_mfma_f32_16x16x32_bf16 v[22:25], v[154:157], v[210:213], v[22:25]
	v_mfma_f32_16x16x32_bf16 v[14:17], v[162:165], v[210:213], v[14:17]
	v_mfma_f32_16x16x32_bf16 v[62:65], v[158:161], v[190:193], v[62:65]
	v_mfma_f32_16x16x32_bf16 v[58:61], v[166:169], v[190:193], v[58:61]
	v_mfma_f32_16x16x32_bf16 v[54:57], v[158:161], v[198:201], v[54:57]
	v_mfma_f32_16x16x32_bf16 v[46:49], v[166:169], v[198:201], v[46:49]
	v_mfma_f32_16x16x32_bf16 v[38:41], v[158:161], v[206:209], v[38:41]
	v_mfma_f32_16x16x32_bf16 v[30:33], v[166:169], v[206:209], v[30:33]
	v_mfma_f32_16x16x32_bf16 v[22:25], v[158:161], v[214:217], v[22:25]
	v_mfma_f32_16x16x32_bf16 v[14:17], v[166:169], v[214:217], v[14:17]
	s_setprio 0
	s_setprio 1
	v_mfma_f32_16x16x32_bf16 v[50:53], v[170:173], v[186:189], v[50:53]
	v_mfma_f32_16x16x32_bf16 v[42:45], v[178:181], v[186:189], v[42:45]
	v_mfma_f32_16x16x32_bf16 v[34:37], v[170:173], v[194:197], v[34:37]
	v_mfma_f32_16x16x32_bf16 v[26:29], v[178:181], v[194:197], v[26:29]
	v_mfma_f32_16x16x32_bf16 v[18:21], v[170:173], v[202:205], v[18:21]
	v_mfma_f32_16x16x32_bf16 v[10:13], v[178:181], v[202:205], v[10:13]
	v_mfma_f32_16x16x32_bf16 v[6:9], v[170:173], v[210:213], v[6:9]
	v_mfma_f32_16x16x32_bf16 v[2:5], v[178:181], v[210:213], v[2:5]
	v_mfma_f32_16x16x32_bf16 v[50:53], v[174:177], v[190:193], v[50:53]
	v_mfma_f32_16x16x32_bf16 v[42:45], v[182:185], v[190:193], v[42:45]
	v_mfma_f32_16x16x32_bf16 v[34:37], v[174:177], v[198:201], v[34:37]
	v_mfma_f32_16x16x32_bf16 v[26:29], v[182:185], v[198:201], v[26:29]
	v_mfma_f32_16x16x32_bf16 v[18:21], v[174:177], v[206:209], v[18:21]
	v_mfma_f32_16x16x32_bf16 v[10:13], v[182:185], v[206:209], v[10:13]
	v_mfma_f32_16x16x32_bf16 v[6:9], v[174:177], v[214:217], v[6:9]
	v_mfma_f32_16x16x32_bf16 v[2:5], v[182:185], v[214:217], v[2:5]
	s_setprio 0
	s_barrier
	s_add_i32 s92, 0, 0x18000
	v_add_u32_e32 v146, s92, v147
	s_add_i32 s93, 0, 0x1c000
	ds_read_b128 v[154:157], v146
	ds_read_b128 v[158:161], v146 offset:1024
	ds_read_b128 v[162:165], v146 offset:2048
	ds_read_b128 v[166:169], v146 offset:3072
	v_add_u32_e32 v146, s93, v147
	ds_read_b128 v[170:173], v146
	ds_read_b128 v[174:177], v146 offset:1024
	ds_read_b128 v[178:181], v146 offset:2048
	ds_read_b128 v[182:185], v146 offset:3072
	s_add_u32 s46, s46, 0x80000
	s_addc_u32 s47, s47, 0
	s_mov_b32 m0, s77
	v_lshl_add_u64 v[226:227], s[46:47], 0, v[136:137]
	ds_read_b128 v[186:189], v153 offset:32768
	ds_read_b128 v[190:193], v153 offset:33792
	ds_read_b128 v[194:197], v153 offset:34816
	ds_read_b128 v[198:201], v153 offset:35840
	ds_read_b128 v[202:205], v153 offset:36864
	ds_read_b128 v[206:209], v153 offset:37888
	ds_read_b128 v[210:213], v153 offset:38912
	ds_read_b128 v[214:217], v153 offset:39936
	global_load_lds_dwordx4 v[226:227], off
	v_lshl_add_u64 v[226:227], s[46:47], 0, v[132:133]
	s_mov_b32 m0, s78
	s_nop 0
	global_load_lds_dwordx4 v[226:227], off
	s_waitcnt vmcnt(8)
	s_waitcnt lgkmcnt(0)
	s_barrier
	s_setprio 1
	s_waitcnt lgkmcnt(0)
	v_mfma_f32_16x16x32_bf16 v[126:129], v[154:157], v[186:189], v[126:129]
	v_mfma_f32_16x16x32_bf16 v[122:125], v[162:165], v[186:189], v[122:125]
	v_mfma_f32_16x16x32_bf16 v[118:121], v[154:157], v[194:197], v[118:121]
	v_mfma_f32_16x16x32_bf16 v[114:117], v[162:165], v[194:197], v[114:117]
	v_mfma_f32_16x16x32_bf16 v[102:105], v[154:157], v[202:205], v[102:105]
	v_mfma_f32_16x16x32_bf16 v[98:101], v[162:165], v[202:205], v[98:101]
	v_mfma_f32_16x16x32_bf16 v[86:89], v[154:157], v[210:213], v[86:89]
	v_mfma_f32_16x16x32_bf16 v[78:81], v[162:165], v[210:213], v[78:81]
	v_mfma_f32_16x16x32_bf16 v[126:129], v[158:161], v[190:193], v[126:129]
	v_mfma_f32_16x16x32_bf16 v[122:125], v[166:169], v[190:193], v[122:125]
	v_mfma_f32_16x16x32_bf16 v[118:121], v[158:161], v[198:201], v[118:121]
	v_mfma_f32_16x16x32_bf16 v[114:117], v[166:169], v[198:201], v[114:117]
	v_mfma_f32_16x16x32_bf16 v[102:105], v[158:161], v[206:209], v[102:105]
	v_mfma_f32_16x16x32_bf16 v[98:101], v[166:169], v[206:209], v[98:101]
	v_mfma_f32_16x16x32_bf16 v[86:89], v[158:161], v[214:217], v[86:89]
	v_mfma_f32_16x16x32_bf16 v[78:81], v[166:169], v[214:217], v[78:81]
	s_setprio 0
	s_setprio 1
	v_mfma_f32_16x16x32_bf16 v[110:113], v[170:173], v[186:189], v[110:113]
	v_mfma_f32_16x16x32_bf16 v[106:109], v[178:181], v[186:189], v[106:109]
	v_mfma_f32_16x16x32_bf16 v[94:97], v[170:173], v[194:197], v[94:97]
	v_mfma_f32_16x16x32_bf16 v[90:93], v[178:181], v[194:197], v[90:93]
	v_mfma_f32_16x16x32_bf16 v[82:85], v[170:173], v[202:205], v[82:85]
	v_mfma_f32_16x16x32_bf16 v[74:77], v[178:181], v[202:205], v[74:77]
	v_mfma_f32_16x16x32_bf16 v[70:73], v[170:173], v[210:213], v[70:73]
	v_mfma_f32_16x16x32_bf16 v[66:69], v[178:181], v[210:213], v[66:69]
	v_mfma_f32_16x16x32_bf16 v[110:113], v[174:177], v[190:193], v[110:113]
	v_mfma_f32_16x16x32_bf16 v[106:109], v[182:185], v[190:193], v[106:109]
	v_mfma_f32_16x16x32_bf16 v[94:97], v[174:177], v[198:201], v[94:97]
	v_mfma_f32_16x16x32_bf16 v[90:93], v[182:185], v[198:201], v[90:93]
	v_mfma_f32_16x16x32_bf16 v[82:85], v[174:177], v[206:209], v[82:85]
	v_mfma_f32_16x16x32_bf16 v[74:77], v[182:185], v[206:209], v[74:77]
	v_mfma_f32_16x16x32_bf16 v[70:73], v[174:177], v[214:217], v[70:73]
	v_mfma_f32_16x16x32_bf16 v[66:69], v[182:185], v[214:217], v[66:69]
	s_setprio 0
	s_barrier
	s_add_i32 s46, s92, s53
	v_lshl_add_u64 v[218:219], v[218:219], 0, s[14:15]
	s_mov_b32 m0, s46
	ds_read_b128 v[186:189], v153 offset:49152
	ds_read_b128 v[190:193], v153 offset:50176
	ds_read_b128 v[194:197], v153 offset:51200
	ds_read_b128 v[198:201], v153 offset:52224
	ds_read_b128 v[202:205], v153 offset:53248
	ds_read_b128 v[206:209], v153 offset:54272
	ds_read_b128 v[210:213], v153 offset:55296
	ds_read_b128 v[214:217], v153 offset:56320
	global_load_lds_dwordx4 v[218:219], off
	s_add_i32 m0, s46, 0x2000
	s_add_u32 s30, s30, 0x80080
	v_lshl_add_u64 v[218:219], v[220:221], 0, s[14:15]
	s_addc_u32 s31, s31, 0
	s_add_i32 s46, s93, s53
	global_load_lds_dwordx4 v[218:219], off
	v_lshl_add_u64 v[218:219], s[30:31], 0, v[134:135]
	s_mov_b32 m0, s46
	s_nop 0
	global_load_lds_dwordx4 v[218:219], off
	v_lshl_add_u64 v[218:219], s[30:31], 0, v[130:131]
	s_add_i32 m0, s46, 0x2000
	s_nop 0
	global_load_lds_dwordx4 v[218:219], off
	v_lshl_add_u64 v[218:219], v[222:223], 0, s[14:15]
	s_mov_b32 m0, s81
	s_nop 0
	global_load_lds_dwordx4 v[218:219], off
	v_lshl_add_u64 v[218:219], v[224:225], 0, s[14:15]
	s_mov_b32 m0, s82
	s_nop 0
	global_load_lds_dwordx4 v[218:219], off
	s_waitcnt vmcnt(8)
	s_waitcnt lgkmcnt(0)
	s_barrier
	s_setprio 1
	s_waitcnt lgkmcnt(0)
	v_mfma_f32_16x16x32_bf16 v[62:65], v[154:157], v[186:189], v[62:65]
	v_mfma_f32_16x16x32_bf16 v[58:61], v[162:165], v[186:189], v[58:61]
	v_mfma_f32_16x16x32_bf16 v[54:57], v[154:157], v[194:197], v[54:57]
	v_mfma_f32_16x16x32_bf16 v[46:49], v[162:165], v[194:197], v[46:49]
	v_mfma_f32_16x16x32_bf16 v[38:41], v[154:157], v[202:205], v[38:41]
	v_mfma_f32_16x16x32_bf16 v[30:33], v[162:165], v[202:205], v[30:33]
	v_mfma_f32_16x16x32_bf16 v[22:25], v[154:157], v[210:213], v[22:25]
	v_mfma_f32_16x16x32_bf16 v[14:17], v[162:165], v[210:213], v[14:17]
	v_mfma_f32_16x16x32_bf16 v[62:65], v[158:161], v[190:193], v[62:65]
	v_mfma_f32_16x16x32_bf16 v[58:61], v[166:169], v[190:193], v[58:61]
	v_mfma_f32_16x16x32_bf16 v[54:57], v[158:161], v[198:201], v[54:57]
	v_mfma_f32_16x16x32_bf16 v[46:49], v[166:169], v[198:201], v[46:49]
	v_mfma_f32_16x16x32_bf16 v[38:41], v[158:161], v[206:209], v[38:41]
	v_mfma_f32_16x16x32_bf16 v[30:33], v[166:169], v[206:209], v[30:33]
	v_mfma_f32_16x16x32_bf16 v[22:25], v[158:161], v[214:217], v[22:25]
	v_mfma_f32_16x16x32_bf16 v[14:17], v[166:169], v[214:217], v[14:17]
	s_setprio 0
	s_setprio 1
	v_mfma_f32_16x16x32_bf16 v[50:53], v[170:173], v[186:189], v[50:53]
	v_mfma_f32_16x16x32_bf16 v[42:45], v[178:181], v[186:189], v[42:45]
	v_mfma_f32_16x16x32_bf16 v[34:37], v[170:173], v[194:197], v[34:37]
	v_mfma_f32_16x16x32_bf16 v[26:29], v[178:181], v[194:197], v[26:29]
	v_mfma_f32_16x16x32_bf16 v[18:21], v[170:173], v[202:205], v[18:21]
	v_mfma_f32_16x16x32_bf16 v[10:13], v[178:181], v[202:205], v[10:13]
	v_mfma_f32_16x16x32_bf16 v[6:9], v[170:173], v[210:213], v[6:9]
	v_mfma_f32_16x16x32_bf16 v[2:5], v[178:181], v[210:213], v[2:5]
	v_mfma_f32_16x16x32_bf16 v[50:53], v[174:177], v[190:193], v[50:53]
	v_mfma_f32_16x16x32_bf16 v[42:45], v[182:185], v[190:193], v[42:45]
	v_mfma_f32_16x16x32_bf16 v[34:37], v[174:177], v[198:201], v[34:37]
	v_mfma_f32_16x16x32_bf16 v[26:29], v[182:185], v[198:201], v[26:29]
	v_mfma_f32_16x16x32_bf16 v[18:21], v[174:177], v[206:209], v[18:21]
	v_mfma_f32_16x16x32_bf16 v[10:13], v[182:185], v[206:209], v[10:13]
	v_mfma_f32_16x16x32_bf16 v[6:9], v[174:177], v[214:217], v[6:9]
	v_mfma_f32_16x16x32_bf16 v[2:5], v[182:185], v[214:217], v[2:5]
	s_setprio 0
	s_add_i32 s91, s91, 2
	s_add_u32 s28, s28, 0x100
	s_addc_u32 s29, s29, 0
	s_add_u32 s89, s89, 0x100
	s_addc_u32 s90, s90, 0
	s_cmp_gt_u32 s91, 29
	s_barrier
	s_cbranch_scc0 .LBB0_122
	s_and_b64 vcc, exec, s[16:17]
	s_cbranch_vccz .LBB0_125
	s_barrier

.LBB0_397:
	v_add_u32_e32 v149, s72, v164
	ds_read_b128 v[170:173], v149
	ds_read_b128 v[174:177], v149 offset:1024
	ds_read_b128 v[178:181], v149 offset:2048
	ds_read_b128 v[182:185], v149 offset:3072
	v_add_u32_e32 v149, s73, v164
	ds_read_b128 v[186:189], v149
	ds_read_b128 v[190:193], v149 offset:1024
	ds_read_b128 v[194:197], v149 offset:2048
	ds_read_b128 v[198:201], v149 offset:3072
	s_mov_b32 s74, 0xfff80080
	s_cmp_eq_u32 s43, 28
	s_mov_b32 s75, -1
	v_lshl_add_u64 v[202:203], v[160:161], 0, s[74:75]
	s_cselect_b64 vcc, -1, 0
	v_cndmask_b32_e32 v235, v203, v131, vcc
	v_cndmask_b32_e32 v234, v202, v156, vcc
	v_cndmask_b32_e32 v237, v163, v141, vcc
	v_cndmask_b32_e32 v236, v162, v158, vcc
	s_mov_b32 m0, s83
	v_lshl_add_u64 v[238:239], v[160:161], 0, v[142:143]
	ds_read_b128 v[202:205], v166
	ds_read_b128 v[206:209], v166 offset:1024
	ds_read_b128 v[210:213], v166 offset:2048
	ds_read_b128 v[214:217], v166 offset:3072
	ds_read_b128 v[218:221], v166 offset:4096
	ds_read_b128 v[222:225], v166 offset:5120
	ds_read_b128 v[226:229], v166 offset:6144
	ds_read_b128 v[230:233], v166 offset:7168
	global_load_lds_dwordx4 v[238:239], off
	v_lshl_add_u64 v[238:239], v[160:161], 0, v[144:145]
	s_mov_b32 m0, s84
	s_nop 0
	global_load_lds_dwordx4 v[238:239], off
	s_waitcnt vmcnt(8)
	s_waitcnt lgkmcnt(0)
	s_barrier
	s_setprio 1
	s_waitcnt lgkmcnt(0)
	v_mfma_f32_16x16x32_bf16 v[126:129], v[170:173], v[202:205], v[126:129]
	v_mfma_f32_16x16x32_bf16 v[122:125], v[178:181], v[202:205], v[122:125]
	v_mfma_f32_16x16x32_bf16 v[118:121], v[170:173], v[210:213], v[118:121]
	v_mfma_f32_16x16x32_bf16 v[114:117], v[178:181], v[210:213], v[114:117]
	v_mfma_f32_16x16x32_bf16 v[106:109], v[170:173], v[218:221], v[106:109]
	v_mfma_f32_16x16x32_bf16 v[98:101], v[178:181], v[218:221], v[98:101]
	v_mfma_f32_16x16x32_bf16 v[78:81], v[170:173], v[226:229], v[78:81]
	v_mfma_f32_16x16x32_bf16 v[74:77], v[178:181], v[226:229], v[74:77]
	v_mfma_f32_16x16x32_bf16 v[126:129], v[174:177], v[206:209], v[126:129]
	v_mfma_f32_16x16x32_bf16 v[122:125], v[182:185], v[206:209], v[122:125]
	v_mfma_f32_16x16x32_bf16 v[118:121], v[174:177], v[214:217], v[118:121]
	v_mfma_f32_16x16x32_bf16 v[114:117], v[182:185], v[214:217], v[114:117]
	v_mfma_f32_16x16x32_bf16 v[106:109], v[174:177], v[222:225], v[106:109]
	v_mfma_f32_16x16x32_bf16 v[98:101], v[182:185], v[222:225], v[98:101]
	v_mfma_f32_16x16x32_bf16 v[78:81], v[174:177], v[230:233], v[78:81]
	v_mfma_f32_16x16x32_bf16 v[74:77], v[182:185], v[230:233], v[74:77]
	s_setprio 0
	s_setprio 1
	v_mfma_f32_16x16x32_bf16 v[110:113], v[186:189], v[202:205], v[110:113]
	v_mfma_f32_16x16x32_bf16 v[102:105], v[194:197], v[202:205], v[102:105]
	v_mfma_f32_16x16x32_bf16 v[94:97], v[186:189], v[210:213], v[94:97]
	v_mfma_f32_16x16x32_bf16 v[90:93], v[194:197], v[210:213], v[90:93]
	v_mfma_f32_16x16x32_bf16 v[86:89], v[186:189], v[218:221], v[86:89]
	v_mfma_f32_16x16x32_bf16 v[82:85], v[194:197], v[218:221], v[82:85]
	v_mfma_f32_16x16x32_bf16 v[70:73], v[186:189], v[226:229], v[70:73]
	v_mfma_f32_16x16x32_bf16 v[66:69], v[194:197], v[226:229], v[66:69]
	v_mfma_f32_16x16x32_bf16 v[110:113], v[190:193], v[206:209], v[110:113]
	v_mfma_f32_16x16x32_bf16 v[102:105], v[198:201], v[206:209], v[102:105]
	v_mfma_f32_16x16x32_bf16 v[94:97], v[190:193], v[214:217], v[94:97]
	v_mfma_f32_16x16x32_bf16 v[90:93], v[198:201], v[214:217], v[90:93]
	v_mfma_f32_16x16x32_bf16 v[86:89], v[190:193], v[222:225], v[86:89]
	v_mfma_f32_16x16x32_bf16 v[82:85], v[198:201], v[222:225], v[82:85]
	v_mfma_f32_16x16x32_bf16 v[70:73], v[190:193], v[230:233], v[70:73]
	v_mfma_f32_16x16x32_bf16 v[66:69], v[198:201], v[230:233], v[66:69]
	s_setprio 0
	s_barrier
	s_mov_b32 m0, s85
	v_lshl_add_u64 v[238:239], v[236:237], 0, v[136:137]
	ds_read_b128 v[202:205], v166 offset:16384
	ds_read_b128 v[206:209], v166 offset:17408
	ds_read_b128 v[210:213], v166 offset:18432
	ds_read_b128 v[214:217], v166 offset:19456
	ds_read_b128 v[218:221], v166 offset:20480
	ds_read_b128 v[222:225], v166 offset:21504
	ds_read_b128 v[226:229], v166 offset:22528
	ds_read_b128 v[230:233], v166 offset:23552
	global_load_lds_dwordx4 v[238:239], off
	v_lshl_add_u64 v[240:241], v[236:237], 0, v[132:133]
	s_mov_b32 m0, s86
	v_lshl_add_u64 v[242:243], v[236:237], 0, s[14:15]
	global_load_lds_dwordx4 v[240:241], off
	v_lshl_add_u64 v[244:245], v[242:243], 0, v[136:137]
	s_mov_b32 m0, s87
	v_lshl_add_u64 v[242:243], v[242:243], 0, v[132:133]
	global_load_lds_dwordx4 v[244:245], off
	s_mov_b32 m0, s88
	v_lshl_add_u64 v[244:245], v[234:235], 0, v[134:135]
	global_load_lds_dwordx4 v[242:243], off
	v_lshl_add_u64 v[242:243], v[234:235], 0, v[138:139]
	s_mov_b32 m0, s12
	s_nop 0
	global_load_lds_dwordx4 v[242:243], off
	s_mov_b32 m0, s78
	s_nop 0
	global_load_lds_dwordx4 v[244:245], off
	s_waitcnt vmcnt(8)
	s_waitcnt lgkmcnt(0)
	s_barrier
	s_setprio 1
	s_waitcnt lgkmcnt(0)
	v_mfma_f32_16x16x32_bf16 v[62:65], v[170:173], v[202:205], v[62:65]
	v_mfma_f32_16x16x32_bf16 v[58:61], v[178:181], v[202:205], v[58:61]
	v_mfma_f32_16x16x32_bf16 v[54:57], v[170:173], v[210:213], v[54:57]
	v_mfma_f32_16x16x32_bf16 v[46:49], v[178:181], v[210:213], v[46:49]
	v_mfma_f32_16x16x32_bf16 v[38:41], v[170:173], v[218:221], v[38:41]
	v_mfma_f32_16x16x32_bf16 v[30:33], v[178:181], v[218:221], v[30:33]
	v_mfma_f32_16x16x32_bf16 v[22:25], v[170:173], v[226:229], v[22:25]
	v_mfma_f32_16x16x32_bf16 v[14:17], v[178:181], v[226:229], v[14:17]
	v_mfma_f32_16x16x32_bf16 v[62:65], v[174:177], v[206:209], v[62:65]
	v_mfma_f32_16x16x32_bf16 v[58:61], v[182:185], v[206:209], v[58:61]
	v_mfma_f32_16x16x32_bf16 v[54:57], v[174:177], v[214:217], v[54:57]
	v_mfma_f32_16x16x32_bf16 v[46:49], v[182:185], v[214:217], v[46:49]
	v_mfma_f32_16x16x32_bf16 v[38:41], v[174:177], v[222:225], v[38:41]
	v_mfma_f32_16x16x32_bf16 v[30:33], v[182:185], v[222:225], v[30:33]
	v_mfma_f32_16x16x32_bf16 v[22:25], v[174:177], v[230:233], v[22:25]
	v_mfma_f32_16x16x32_bf16 v[14:17], v[182:185], v[230:233], v[14:17]
	s_setprio 0
	s_setprio 1
	v_mfma_f32_16x16x32_bf16 v[50:53], v[186:189], v[202:205], v[50:53]
	v_mfma_f32_16x16x32_bf16 v[42:45], v[194:197], v[202:205], v[42:45]
	v_mfma_f32_16x16x32_bf16 v[34:37], v[186:189], v[210:213], v[34:37]
	v_mfma_f32_16x16x32_bf16 v[26:29], v[194:197], v[210:213], v[26:29]
	v_mfma_f32_16x16x32_bf16 v[18:21], v[186:189], v[218:221], v[18:21]
	v_mfma_f32_16x16x32_bf16 v[10:13], v[194:197], v[218:221], v[10:13]
	v_mfma_f32_16x16x32_bf16 v[6:9], v[186:189], v[226:229], v[6:9]
	v_mfma_f32_16x16x32_bf16 v[2:5], v[194:197], v[226:229], v[2:5]
	v_mfma_f32_16x16x32_bf16 v[50:53], v[190:193], v[206:209], v[50:53]
	v_mfma_f32_16x16x32_bf16 v[42:45], v[198:201], v[206:209], v[42:45]
	v_mfma_f32_16x16x32_bf16 v[34:37], v[190:193], v[214:217], v[34:37]
	v_mfma_f32_16x16x32_bf16 v[26:29], v[198:201], v[214:217], v[26:29]
	v_mfma_f32_16x16x32_bf16 v[18:21], v[190:193], v[222:225], v[18:21]
	v_mfma_f32_16x16x32_bf16 v[10:13], v[198:201], v[222:225], v[10:13]
	v_mfma_f32_16x16x32_bf16 v[6:9], v[190:193], v[230:233], v[6:9]
	v_mfma_f32_16x16x32_bf16 v[2:5], v[198:201], v[230:233], v[2:5]
	s_setprio 0
	s_barrier
	v_add_u32_e32 v149, s89, v164
	ds_read_b128 v[170:173], v149
	ds_read_b128 v[174:177], v149 offset:1024
	ds_read_b128 v[178:181], v149 offset:2048
	ds_read_b128 v[182:185], v149 offset:3072
	v_add_u32_e32 v149, s90, v164
	ds_read_b128 v[186:189], v149
	ds_read_b128 v[190:193], v149 offset:1024
	ds_read_b128 v[194:197], v149 offset:2048
	ds_read_b128 v[198:201], v149 offset:3072
	v_lshl_add_u64 v[234:235], v[234:235], 0, s[14:15]
	s_mov_b32 m0, s79
	v_lshl_add_u64 v[246:247], v[234:235], 0, v[138:139]
	ds_read_b128 v[202:205], v166 offset:32768
	ds_read_b128 v[206:209], v166 offset:33792
	ds_read_b128 v[210:213], v166 offset:34816
	ds_read_b128 v[214:217], v166 offset:35840
	ds_read_b128 v[218:221], v166 offset:36864
	ds_read_b128 v[222:225], v166 offset:37888
	ds_read_b128 v[226:229], v166 offset:38912
	ds_read_b128 v[230:233], v166 offset:39936
	global_load_lds_dwordx4 v[246:247], off
	v_lshl_add_u64 v[234:235], v[234:235], 0, v[134:135]
	s_mov_b32 m0, s80
	s_nop 0
	global_load_lds_dwordx4 v[234:235], off
	s_waitcnt vmcnt(8)
	s_waitcnt lgkmcnt(0)
	s_barrier
	s_setprio 1
	s_waitcnt lgkmcnt(0)
	v_mfma_f32_16x16x32_bf16 v[126:129], v[170:173], v[202:205], v[126:129]
	v_mfma_f32_16x16x32_bf16 v[122:125], v[178:181], v[202:205], v[122:125]
	v_mfma_f32_16x16x32_bf16 v[118:121], v[170:173], v[210:213], v[118:121]
	v_mfma_f32_16x16x32_bf16 v[114:117], v[178:181], v[210:213], v[114:117]
	v_mfma_f32_16x16x32_bf16 v[106:109], v[170:173], v[218:221], v[106:109]
	v_mfma_f32_16x16x32_bf16 v[98:101], v[178:181], v[218:221], v[98:101]
	v_mfma_f32_16x16x32_bf16 v[78:81], v[170:173], v[226:229], v[78:81]
	v_mfma_f32_16x16x32_bf16 v[74:77], v[178:181], v[226:229], v[74:77]
	v_mfma_f32_16x16x32_bf16 v[126:129], v[174:177], v[206:209], v[126:129]
	v_mfma_f32_16x16x32_bf16 v[122:125], v[182:185], v[206:209], v[122:125]
	v_mfma_f32_16x16x32_bf16 v[118:121], v[174:177], v[214:217], v[118:121]
	v_mfma_f32_16x16x32_bf16 v[114:117], v[182:185], v[214:217], v[114:117]
	v_mfma_f32_16x16x32_bf16 v[106:109], v[174:177], v[222:225], v[106:109]
	v_mfma_f32_16x16x32_bf16 v[98:101], v[182:185], v[222:225], v[98:101]
	v_mfma_f32_16x16x32_bf16 v[78:81], v[174:177], v[230:233], v[78:81]
	v_mfma_f32_16x16x32_bf16 v[74:77], v[182:185], v[230:233], v[74:77]
	s_setprio 0
	s_setprio 1
	v_mfma_f32_16x16x32_bf16 v[110:113], v[186:189], v[202:205], v[110:113]
	v_mfma_f32_16x16x32_bf16 v[102:105], v[194:197], v[202:205], v[102:105]
	v_mfma_f32_16x16x32_bf16 v[94:97], v[186:189], v[210:213], v[94:97]
	v_mfma_f32_16x16x32_bf16 v[90:93], v[194:197], v[210:213], v[90:93]
	v_mfma_f32_16x16x32_bf16 v[86:89], v[186:189], v[218:221], v[86:89]
	v_mfma_f32_16x16x32_bf16 v[82:85], v[194:197], v[218:221], v[82:85]
	v_mfma_f32_16x16x32_bf16 v[70:73], v[186:189], v[226:229], v[70:73]
	v_mfma_f32_16x16x32_bf16 v[66:69], v[194:197], v[226:229], v[66:69]
	v_mfma_f32_16x16x32_bf16 v[110:113], v[190:193], v[206:209], v[110:113]
	v_mfma_f32_16x16x32_bf16 v[102:105], v[198:201], v[206:209], v[102:105]
	v_mfma_f32_16x16x32_bf16 v[94:97], v[190:193], v[214:217], v[94:97]
	v_mfma_f32_16x16x32_bf16 v[90:93], v[198:201], v[214:217], v[90:93]
	v_mfma_f32_16x16x32_bf16 v[86:89], v[190:193], v[222:225], v[86:89]
	v_mfma_f32_16x16x32_bf16 v[82:85], v[198:201], v[222:225], v[82:85]
	v_mfma_f32_16x16x32_bf16 v[70:73], v[190:193], v[230:233], v[70:73]
	v_mfma_f32_16x16x32_bf16 v[66:69], v[198:201], v[230:233], v[66:69]
	s_setprio 0
	s_barrier
	s_mov_b32 m0, s95
	v_lshl_add_u64 v[234:235], v[238:239], 0, s[22:23]
	ds_read_b128 v[202:205], v166 offset:49152
	ds_read_b128 v[206:209], v166 offset:50176
	ds_read_b128 v[210:213], v166 offset:51200
	ds_read_b128 v[214:217], v166 offset:52224
	ds_read_b128 v[218:221], v166 offset:53248
	ds_read_b128 v[222:225], v166 offset:54272
	ds_read_b128 v[226:229], v166 offset:55296
	ds_read_b128 v[230:233], v166 offset:56320
	global_load_lds_dwordx4 v[234:235], off
	v_lshl_add_u64 v[234:235], v[240:241], 0, s[22:23]
	s_mov_b32 m0, s96
	s_nop 0
	global_load_lds_dwordx4 v[234:235], off
	v_lshl_add_u64 v[234:235], v[236:237], 0, s[24:25]
	v_lshl_add_u64 v[236:237], v[234:235], 0, v[136:137]
	s_mov_b32 m0, s97
	v_lshl_add_u64 v[234:235], v[234:235], 0, v[132:133]
	global_load_lds_dwordx4 v[236:237], off
	s_mov_b32 m0, s42
	s_nop 0
	global_load_lds_dwordx4 v[234:235], off
	v_lshl_add_u64 v[234:235], v[242:243], 0, s[22:23]
	s_mov_b32 m0, s81
	s_nop 0
	global_load_lds_dwordx4 v[234:235], off
	v_lshl_add_u64 v[234:235], v[244:245], 0, s[22:23]
	s_mov_b32 m0, s82
	s_nop 0
	global_load_lds_dwordx4 v[234:235], off
	s_waitcnt vmcnt(8)
	s_waitcnt lgkmcnt(0)
	s_barrier
	s_setprio 1
	s_waitcnt lgkmcnt(0)
	v_mfma_f32_16x16x32_bf16 v[62:65], v[170:173], v[202:205], v[62:65]
	v_mfma_f32_16x16x32_bf16 v[58:61], v[178:181], v[202:205], v[58:61]
	v_mfma_f32_16x16x32_bf16 v[54:57], v[170:173], v[210:213], v[54:57]
	v_mfma_f32_16x16x32_bf16 v[46:49], v[178:181], v[210:213], v[46:49]
	v_mfma_f32_16x16x32_bf16 v[38:41], v[170:173], v[218:221], v[38:41]
	v_mfma_f32_16x16x32_bf16 v[30:33], v[178:181], v[218:221], v[30:33]
	v_mfma_f32_16x16x32_bf16 v[22:25], v[170:173], v[226:229], v[22:25]
	v_mfma_f32_16x16x32_bf16 v[14:17], v[178:181], v[226:229], v[14:17]
	v_mfma_f32_16x16x32_bf16 v[62:65], v[174:177], v[206:209], v[62:65]
	v_mfma_f32_16x16x32_bf16 v[58:61], v[182:185], v[206:209], v[58:61]
	v_mfma_f32_16x16x32_bf16 v[54:57], v[174:177], v[214:217], v[54:57]
	v_mfma_f32_16x16x32_bf16 v[46:49], v[182:185], v[214:217], v[46:49]
	v_mfma_f32_16x16x32_bf16 v[38:41], v[174:177], v[222:225], v[38:41]
	v_mfma_f32_16x16x32_bf16 v[30:33], v[182:185], v[222:225], v[30:33]
	v_mfma_f32_16x16x32_bf16 v[22:25], v[174:177], v[230:233], v[22:25]
	v_mfma_f32_16x16x32_bf16 v[14:17], v[182:185], v[230:233], v[14:17]
	s_setprio 0
	s_setprio 1
	v_mfma_f32_16x16x32_bf16 v[50:53], v[186:189], v[202:205], v[50:53]
	v_mfma_f32_16x16x32_bf16 v[42:45], v[194:197], v[202:205], v[42:45]
	v_mfma_f32_16x16x32_bf16 v[34:37], v[186:189], v[210:213], v[34:37]
	v_mfma_f32_16x16x32_bf16 v[26:29], v[194:197], v[210:213], v[26:29]
	v_mfma_f32_16x16x32_bf16 v[18:21], v[186:189], v[218:221], v[18:21]
	v_mfma_f32_16x16x32_bf16 v[10:13], v[194:197], v[218:221], v[10:13]
	v_mfma_f32_16x16x32_bf16 v[6:9], v[186:189], v[226:229], v[6:9]
	v_mfma_f32_16x16x32_bf16 v[2:5], v[194:197], v[226:229], v[2:5]
	v_mfma_f32_16x16x32_bf16 v[50:53], v[190:193], v[206:209], v[50:53]
	v_mfma_f32_16x16x32_bf16 v[42:45], v[198:201], v[206:209], v[42:45]
	v_mfma_f32_16x16x32_bf16 v[34:37], v[190:193], v[214:217], v[34:37]
	v_mfma_f32_16x16x32_bf16 v[26:29], v[198:201], v[214:217], v[26:29]
	v_mfma_f32_16x16x32_bf16 v[18:21], v[190:193], v[222:225], v[18:21]
	v_mfma_f32_16x16x32_bf16 v[10:13], v[198:201], v[222:225], v[10:13]
	v_mfma_f32_16x16x32_bf16 v[6:9], v[190:193], v[230:233], v[6:9]
	v_mfma_f32_16x16x32_bf16 v[2:5], v[198:201], v[230:233], v[2:5]
	s_setprio 0
	s_add_i32 s43, s43, 2
	v_lshl_add_u64 v[160:161], v[160:161], 0, s[30:31]
	s_cmp_gt_u32 s43, 29
	v_lshl_add_u64 v[162:163], v[162:163], 0, s[30:31]
	s_barrier
	s_cbranch_scc0 .LBB0_397
	s_and_b64 vcc, exec, s[26:27]
	s_cbranch_vccz .LBB0_400
	s_barrier

.LBB0_702:
	ds_read_b128 v[130:133], v176
	ds_read_b128 v[134:137], v176 offset:1024
	ds_read_b128 v[138:141], v176 offset:2048
	ds_read_b128 v[150:153], v176 offset:3072
	ds_read_b128 v[162:165], v177
	ds_read_b128 v[180:183], v177 offset:1024
	ds_read_b128 v[184:187], v177 offset:2048
	ds_read_b128 v[188:191], v177 offset:3072
	s_add_u32 s12, s10, 0xfffc0080
	s_addc_u32 s13, s11, -1
	s_cmp_eq_u32 s82, 12
	s_cselect_b32 s15, s43, s13
	s_cselect_b32 s14, s72, s12
	s_cselect_b32 s13, s31, s81
	s_cselect_b32 s12, s73, s80
	v_lshl_add_u64 v[224:225], s[10:11], 0, v[142:143]
	s_add_i32 m0, s64, 0xc000
	ds_read_b128 v[192:195], v178
	ds_read_b128 v[196:199], v178 offset:1024
	ds_read_b128 v[200:203], v178 offset:2048
	ds_read_b128 v[204:207], v178 offset:3072
	ds_read_b128 v[208:211], v178 offset:4096
	ds_read_b128 v[212:215], v178 offset:5120
	ds_read_b128 v[216:219], v178 offset:6144
	ds_read_b128 v[220:223], v178 offset:7168
	global_load_lds_dwordx4 v[224:225], off
	v_lshl_add_u64 v[224:225], s[10:11], 0, v[144:145]
	s_add_i32 m0, s64, 0xe000
	s_nop 0
	global_load_lds_dwordx4 v[224:225], off
	s_waitcnt vmcnt(8)
	s_waitcnt lgkmcnt(0)
	s_barrier
	s_setprio 1
	s_waitcnt lgkmcnt(0)
	v_mfma_f32_16x16x32_bf16 v[126:129], v[130:133], v[192:195], v[126:129]
	v_mfma_f32_16x16x32_bf16 v[122:125], v[138:141], v[192:195], v[122:125]
	v_mfma_f32_16x16x32_bf16 v[110:113], v[130:133], v[200:203], v[110:113]
	v_mfma_f32_16x16x32_bf16 v[106:109], v[138:141], v[200:203], v[106:109]
	v_mfma_f32_16x16x32_bf16 v[94:97], v[130:133], v[208:211], v[94:97]
	v_mfma_f32_16x16x32_bf16 v[90:93], v[138:141], v[208:211], v[90:93]
	v_mfma_f32_16x16x32_bf16 v[78:81], v[130:133], v[216:219], v[78:81]
	v_mfma_f32_16x16x32_bf16 v[74:77], v[138:141], v[216:219], v[74:77]
	v_mfma_f32_16x16x32_bf16 v[126:129], v[134:137], v[196:199], v[126:129]
	v_mfma_f32_16x16x32_bf16 v[122:125], v[150:153], v[196:199], v[122:125]
	v_mfma_f32_16x16x32_bf16 v[110:113], v[134:137], v[204:207], v[110:113]
	v_mfma_f32_16x16x32_bf16 v[106:109], v[150:153], v[204:207], v[106:109]
	v_mfma_f32_16x16x32_bf16 v[94:97], v[134:137], v[212:215], v[94:97]
	v_mfma_f32_16x16x32_bf16 v[90:93], v[150:153], v[212:215], v[90:93]
	v_mfma_f32_16x16x32_bf16 v[78:81], v[134:137], v[220:223], v[78:81]
	v_mfma_f32_16x16x32_bf16 v[74:77], v[150:153], v[220:223], v[74:77]
	s_setprio 0
	s_setprio 1
	v_mfma_f32_16x16x32_bf16 v[118:121], v[162:165], v[192:195], v[118:121]
	v_mfma_f32_16x16x32_bf16 v[114:117], v[184:187], v[192:195], v[114:117]
	v_mfma_f32_16x16x32_bf16 v[102:105], v[162:165], v[200:203], v[102:105]
	v_mfma_f32_16x16x32_bf16 v[98:101], v[184:187], v[200:203], v[98:101]
	v_mfma_f32_16x16x32_bf16 v[86:89], v[162:165], v[208:211], v[86:89]
	v_mfma_f32_16x16x32_bf16 v[82:85], v[184:187], v[208:211], v[82:85]
	v_mfma_f32_16x16x32_bf16 v[70:73], v[162:165], v[216:219], v[70:73]
	v_mfma_f32_16x16x32_bf16 v[66:69], v[184:187], v[216:219], v[66:69]
	v_mfma_f32_16x16x32_bf16 v[118:121], v[180:183], v[196:199], v[118:121]
	v_mfma_f32_16x16x32_bf16 v[114:117], v[188:191], v[196:199], v[114:117]
	v_mfma_f32_16x16x32_bf16 v[102:105], v[180:183], v[204:207], v[102:105]
	v_mfma_f32_16x16x32_bf16 v[98:101], v[188:191], v[204:207], v[98:101]
	v_mfma_f32_16x16x32_bf16 v[86:89], v[180:183], v[212:215], v[86:89]
	v_mfma_f32_16x16x32_bf16 v[82:85], v[188:191], v[212:215], v[82:85]
	v_mfma_f32_16x16x32_bf16 v[70:73], v[180:183], v[220:223], v[70:73]
	v_mfma_f32_16x16x32_bf16 v[66:69], v[188:191], v[220:223], v[66:69]
	s_setprio 0
	s_barrier
	s_add_i32 s83, s78, s63
	v_lshl_add_u64 v[224:225], s[12:13], 0, v[156:157]
	s_mov_b32 m0, s83
	ds_read_b128 v[192:195], v178 offset:16384
	ds_read_b128 v[196:199], v178 offset:17408
	ds_read_b128 v[200:203], v178 offset:18432
	ds_read_b128 v[204:207], v178 offset:19456
	ds_read_b128 v[208:211], v178 offset:20480
	ds_read_b128 v[212:215], v178 offset:21504
	ds_read_b128 v[216:219], v178 offset:22528
	ds_read_b128 v[220:223], v178 offset:23552
	global_load_lds_dwordx4 v[224:225], off
	s_add_i32 m0, s83, 0x2000
	s_add_u32 s84, s12, 0x40000
	v_lshl_add_u64 v[226:227], s[12:13], 0, v[160:161]
	s_addc_u32 s85, s13, 0
	s_add_i32 s83, s79, s63
	global_load_lds_dwordx4 v[226:227], off
	v_lshl_add_u64 v[228:229], s[84:85], 0, v[156:157]
	s_mov_b32 m0, s83
	v_lshl_add_u64 v[230:231], s[14:15], 0, v[158:159]
	global_load_lds_dwordx4 v[228:229], off
	v_lshl_add_u64 v[228:229], s[84:85], 0, v[160:161]
	s_add_i32 m0, s83, 0x2000
	s_nop 0
	global_load_lds_dwordx4 v[228:229], off
	v_lshl_add_u64 v[228:229], s[14:15], 0, v[154:155]
	s_mov_b32 m0, s64
	s_nop 0
	global_load_lds_dwordx4 v[228:229], off
	s_mov_b32 m0, s65
	s_nop 0
	global_load_lds_dwordx4 v[230:231], off
	s_waitcnt vmcnt(8)
	s_waitcnt lgkmcnt(0)
	s_barrier
	s_setprio 1
	s_waitcnt lgkmcnt(0)
	v_mfma_f32_16x16x32_bf16 v[62:65], v[130:133], v[192:195], v[62:65]
	v_mfma_f32_16x16x32_bf16 v[58:61], v[138:141], v[192:195], v[58:61]
	v_mfma_f32_16x16x32_bf16 v[46:49], v[130:133], v[200:203], v[46:49]
	v_mfma_f32_16x16x32_bf16 v[42:45], v[138:141], v[200:203], v[42:45]
	v_mfma_f32_16x16x32_bf16 v[30:33], v[130:133], v[208:211], v[30:33]
	v_mfma_f32_16x16x32_bf16 v[26:29], v[138:141], v[208:211], v[26:29]
	v_mfma_f32_16x16x32_bf16 v[14:17], v[130:133], v[216:219], v[14:17]
	v_mfma_f32_16x16x32_bf16 v[10:13], v[138:141], v[216:219], v[10:13]
	v_mfma_f32_16x16x32_bf16 v[62:65], v[134:137], v[196:199], v[62:65]
	v_mfma_f32_16x16x32_bf16 v[58:61], v[150:153], v[196:199], v[58:61]
	v_mfma_f32_16x16x32_bf16 v[46:49], v[134:137], v[204:207], v[46:49]
	v_mfma_f32_16x16x32_bf16 v[42:45], v[150:153], v[204:207], v[42:45]
	v_mfma_f32_16x16x32_bf16 v[30:33], v[134:137], v[212:215], v[30:33]
	v_mfma_f32_16x16x32_bf16 v[26:29], v[150:153], v[212:215], v[26:29]
	v_mfma_f32_16x16x32_bf16 v[14:17], v[134:137], v[220:223], v[14:17]
	v_mfma_f32_16x16x32_bf16 v[10:13], v[150:153], v[220:223], v[10:13]
	s_setprio 0
	s_setprio 1
	v_mfma_f32_16x16x32_bf16 v[54:57], v[162:165], v[192:195], v[54:57]
	v_mfma_f32_16x16x32_bf16 v[50:53], v[184:187], v[192:195], v[50:53]
	v_mfma_f32_16x16x32_bf16 v[38:41], v[162:165], v[200:203], v[38:41]
	v_mfma_f32_16x16x32_bf16 v[34:37], v[184:187], v[200:203], v[34:37]
	v_mfma_f32_16x16x32_bf16 v[22:25], v[162:165], v[208:211], v[22:25]
	v_mfma_f32_16x16x32_bf16 v[18:21], v[184:187], v[208:211], v[18:21]
	v_mfma_f32_16x16x32_bf16 v[6:9], v[162:165], v[216:219], v[6:9]
	v_mfma_f32_16x16x32_bf16 v[2:5], v[184:187], v[216:219], v[2:5]
	v_mfma_f32_16x16x32_bf16 v[54:57], v[180:183], v[196:199], v[54:57]
	v_mfma_f32_16x16x32_bf16 v[50:53], v[188:191], v[196:199], v[50:53]
	v_mfma_f32_16x16x32_bf16 v[38:41], v[180:183], v[204:207], v[38:41]
	v_mfma_f32_16x16x32_bf16 v[34:37], v[188:191], v[204:207], v[34:37]
	v_mfma_f32_16x16x32_bf16 v[22:25], v[180:183], v[212:215], v[22:25]
	v_mfma_f32_16x16x32_bf16 v[18:21], v[188:191], v[212:215], v[18:21]
	v_mfma_f32_16x16x32_bf16 v[6:9], v[180:183], v[220:223], v[6:9]
	v_mfma_f32_16x16x32_bf16 v[2:5], v[188:191], v[220:223], v[2:5]
	s_setprio 0
	s_barrier
	s_add_i32 s83, 0, 0x18000
	s_add_i32 s84, 0, 0x1c000
	v_add_u32_e32 v150, s83, v174
	v_add_u32_e32 v179, s84, v174
	ds_read_b128 v[130:133], v150
	ds_read_b128 v[134:137], v150 offset:1024
	ds_read_b128 v[138:141], v150 offset:2048
	ds_read_b128 v[150:153], v150 offset:3072
	ds_read_b128 v[162:165], v179
	ds_read_b128 v[180:183], v179 offset:1024
	ds_read_b128 v[184:187], v179 offset:2048
	ds_read_b128 v[188:191], v179 offset:3072
	s_add_u32 s14, s14, 0x40000
	s_addc_u32 s15, s15, 0
	s_mov_b32 m0, s66
	v_lshl_add_u64 v[232:233], s[14:15], 0, v[154:155]
	ds_read_b128 v[192:195], v178 offset:32768
	ds_read_b128 v[196:199], v178 offset:33792
	ds_read_b128 v[200:203], v178 offset:34816
	ds_read_b128 v[204:207], v178 offset:35840
	ds_read_b128 v[208:211], v178 offset:36864
	ds_read_b128 v[212:215], v178 offset:37888
	ds_read_b128 v[216:219], v178 offset:38912
	ds_read_b128 v[220:223], v178 offset:39936
	global_load_lds_dwordx4 v[232:233], off
	v_lshl_add_u64 v[232:233], s[14:15], 0, v[158:159]
	s_mov_b32 m0, s67
	s_nop 0
	global_load_lds_dwordx4 v[232:233], off
	s_waitcnt vmcnt(8)
	s_waitcnt lgkmcnt(0)
	s_barrier
	s_setprio 1
	s_waitcnt lgkmcnt(0)
	v_mfma_f32_16x16x32_bf16 v[126:129], v[130:133], v[192:195], v[126:129]
	v_mfma_f32_16x16x32_bf16 v[122:125], v[138:141], v[192:195], v[122:125]
	v_mfma_f32_16x16x32_bf16 v[110:113], v[130:133], v[200:203], v[110:113]
	v_mfma_f32_16x16x32_bf16 v[106:109], v[138:141], v[200:203], v[106:109]
	v_mfma_f32_16x16x32_bf16 v[94:97], v[130:133], v[208:211], v[94:97]
	v_mfma_f32_16x16x32_bf16 v[90:93], v[138:141], v[208:211], v[90:93]
	v_mfma_f32_16x16x32_bf16 v[78:81], v[130:133], v[216:219], v[78:81]
	v_mfma_f32_16x16x32_bf16 v[74:77], v[138:141], v[216:219], v[74:77]
	v_mfma_f32_16x16x32_bf16 v[126:129], v[134:137], v[196:199], v[126:129]
	v_mfma_f32_16x16x32_bf16 v[122:125], v[150:153], v[196:199], v[122:125]
	v_mfma_f32_16x16x32_bf16 v[110:113], v[134:137], v[204:207], v[110:113]
	v_mfma_f32_16x16x32_bf16 v[106:109], v[150:153], v[204:207], v[106:109]
	v_mfma_f32_16x16x32_bf16 v[94:97], v[134:137], v[212:215], v[94:97]
	v_mfma_f32_16x16x32_bf16 v[90:93], v[150:153], v[212:215], v[90:93]
	v_mfma_f32_16x16x32_bf16 v[78:81], v[134:137], v[220:223], v[78:81]
	v_mfma_f32_16x16x32_bf16 v[74:77], v[150:153], v[220:223], v[74:77]
	s_setprio 0
	s_setprio 1
	v_mfma_f32_16x16x32_bf16 v[118:121], v[162:165], v[192:195], v[118:121]
	v_mfma_f32_16x16x32_bf16 v[114:117], v[184:187], v[192:195], v[114:117]
	v_mfma_f32_16x16x32_bf16 v[102:105], v[162:165], v[200:203], v[102:105]
	v_mfma_f32_16x16x32_bf16 v[98:101], v[184:187], v[200:203], v[98:101]
	v_mfma_f32_16x16x32_bf16 v[86:89], v[162:165], v[208:211], v[86:89]
	v_mfma_f32_16x16x32_bf16 v[82:85], v[184:187], v[208:211], v[82:85]
	v_mfma_f32_16x16x32_bf16 v[70:73], v[162:165], v[216:219], v[70:73]
	v_mfma_f32_16x16x32_bf16 v[66:69], v[184:187], v[216:219], v[66:69]
	v_mfma_f32_16x16x32_bf16 v[118:121], v[180:183], v[196:199], v[118:121]
	v_mfma_f32_16x16x32_bf16 v[114:117], v[188:191], v[196:199], v[114:117]
	v_mfma_f32_16x16x32_bf16 v[102:105], v[180:183], v[204:207], v[102:105]
	v_mfma_f32_16x16x32_bf16 v[98:101], v[188:191], v[204:207], v[98:101]
	v_mfma_f32_16x16x32_bf16 v[86:89], v[180:183], v[212:215], v[86:89]
	v_mfma_f32_16x16x32_bf16 v[82:85], v[188:191], v[212:215], v[82:85]
	v_mfma_f32_16x16x32_bf16 v[70:73], v[180:183], v[220:223], v[70:73]
	v_mfma_f32_16x16x32_bf16 v[66:69], v[188:191], v[220:223], v[66:69]
	s_setprio 0
	s_barrier
	s_add_i32 s14, s83, s63
	v_lshl_add_u64 v[224:225], v[224:225], 0, s[26:27]
	s_mov_b32 m0, s14
	ds_read_b128 v[192:195], v178 offset:49152
	ds_read_b128 v[196:199], v178 offset:50176
	ds_read_b128 v[200:203], v178 offset:51200
	ds_read_b128 v[204:207], v178 offset:52224
	ds_read_b128 v[208:211], v178 offset:53248
	ds_read_b128 v[212:215], v178 offset:54272
	ds_read_b128 v[216:219], v178 offset:55296
	ds_read_b128 v[220:223], v178 offset:56320
	global_load_lds_dwordx4 v[224:225], off
	s_add_i32 m0, s14, 0x2000
	s_add_u32 s12, s12, 0x40080
	v_lshl_add_u64 v[224:225], v[226:227], 0, s[26:27]
	s_addc_u32 s13, s13, 0
	s_add_i32 s14, s84, s63
	global_load_lds_dwordx4 v[224:225], off
	v_lshl_add_u64 v[224:225], s[12:13], 0, v[156:157]
	s_mov_b32 m0, s14
	s_nop 0
	global_load_lds_dwordx4 v[224:225], off
	v_lshl_add_u64 v[224:225], s[12:13], 0, v[160:161]
	s_add_i32 m0, s14, 0x2000
	s_nop 0
	global_load_lds_dwordx4 v[224:225], off
	v_lshl_add_u64 v[224:225], v[228:229], 0, s[26:27]
	s_mov_b32 m0, s75
	s_nop 0
	global_load_lds_dwordx4 v[224:225], off
	v_lshl_add_u64 v[224:225], v[230:231], 0, s[26:27]
	s_mov_b32 m0, s76
	s_nop 0
	global_load_lds_dwordx4 v[224:225], off
	s_waitcnt vmcnt(8)
	s_waitcnt lgkmcnt(0)
	s_barrier
	s_setprio 1
	s_waitcnt lgkmcnt(0)
	v_mfma_f32_16x16x32_bf16 v[62:65], v[130:133], v[192:195], v[62:65]
	v_mfma_f32_16x16x32_bf16 v[58:61], v[138:141], v[192:195], v[58:61]
	v_mfma_f32_16x16x32_bf16 v[46:49], v[130:133], v[200:203], v[46:49]
	v_mfma_f32_16x16x32_bf16 v[42:45], v[138:141], v[200:203], v[42:45]
	v_mfma_f32_16x16x32_bf16 v[30:33], v[130:133], v[208:211], v[30:33]
	v_mfma_f32_16x16x32_bf16 v[26:29], v[138:141], v[208:211], v[26:29]
	v_mfma_f32_16x16x32_bf16 v[14:17], v[130:133], v[216:219], v[14:17]
	v_mfma_f32_16x16x32_bf16 v[10:13], v[138:141], v[216:219], v[10:13]
	v_mfma_f32_16x16x32_bf16 v[62:65], v[134:137], v[196:199], v[62:65]
	v_mfma_f32_16x16x32_bf16 v[58:61], v[150:153], v[196:199], v[58:61]
	v_mfma_f32_16x16x32_bf16 v[46:49], v[134:137], v[204:207], v[46:49]
	v_mfma_f32_16x16x32_bf16 v[42:45], v[150:153], v[204:207], v[42:45]
	v_mfma_f32_16x16x32_bf16 v[30:33], v[134:137], v[212:215], v[30:33]
	v_mfma_f32_16x16x32_bf16 v[26:29], v[150:153], v[212:215], v[26:29]
	v_mfma_f32_16x16x32_bf16 v[14:17], v[134:137], v[220:223], v[14:17]
	v_mfma_f32_16x16x32_bf16 v[10:13], v[150:153], v[220:223], v[10:13]
	s_setprio 0
	s_setprio 1
	v_mfma_f32_16x16x32_bf16 v[54:57], v[162:165], v[192:195], v[54:57]
	v_mfma_f32_16x16x32_bf16 v[50:53], v[184:187], v[192:195], v[50:53]
	v_mfma_f32_16x16x32_bf16 v[38:41], v[162:165], v[200:203], v[38:41]
	v_mfma_f32_16x16x32_bf16 v[34:37], v[184:187], v[200:203], v[34:37]
	v_mfma_f32_16x16x32_bf16 v[22:25], v[162:165], v[208:211], v[22:25]
	v_mfma_f32_16x16x32_bf16 v[18:21], v[184:187], v[208:211], v[18:21]
	v_mfma_f32_16x16x32_bf16 v[6:9], v[162:165], v[216:219], v[6:9]
	v_mfma_f32_16x16x32_bf16 v[2:5], v[184:187], v[216:219], v[2:5]
	v_mfma_f32_16x16x32_bf16 v[54:57], v[180:183], v[196:199], v[54:57]
	v_mfma_f32_16x16x32_bf16 v[50:53], v[188:191], v[196:199], v[50:53]
	v_mfma_f32_16x16x32_bf16 v[38:41], v[180:183], v[204:207], v[38:41]
	v_mfma_f32_16x16x32_bf16 v[34:37], v[188:191], v[204:207], v[34:37]
	v_mfma_f32_16x16x32_bf16 v[22:25], v[180:183], v[212:215], v[22:25]
	v_mfma_f32_16x16x32_bf16 v[18:21], v[188:191], v[212:215], v[18:21]
	v_mfma_f32_16x16x32_bf16 v[6:9], v[180:183], v[220:223], v[6:9]
	v_mfma_f32_16x16x32_bf16 v[2:5], v[188:191], v[220:223], v[2:5]
	s_setprio 0
	s_add_i32 s82, s82, 2
	s_add_u32 s10, s10, 0x100
	s_addc_u32 s11, s11, 0
	s_add_u32 s80, s80, 0x100
	s_addc_u32 s81, s81, 0
	s_cmp_gt_u32 s82, 13
	s_barrier
	s_cbranch_scc0 .LBB0_702
	s_and_b64 vcc, exec, s[28:29]
	s_cbranch_vccz .LBB0_705
	s_barrier

.LBB0_726:
	ds_read_b128 v[130:133], v1
	ds_read_b128 v[134:137], v1 offset:1024
	ds_read_b128 v[138:141], v1 offset:2048
	ds_read_b128 v[142:145], v1 offset:3072
	ds_read_b128 v[146:149], v181
	ds_read_b128 v[150:153], v181 offset:1024
	ds_read_b128 v[170:173], v181 offset:2048
	ds_read_b128 v[174:177], v181 offset:3072
	s_add_u32 s44, s10, 0xfffc0080
	s_addc_u32 s45, s11, -1
	s_cmp_eq_u32 s83, 12
	s_cselect_b32 s47, s29, s45
	s_cselect_b32 s46, s72, s44
	s_cselect_b32 s45, s27, s82
	s_cselect_b32 s44, s73, s81
	v_lshl_add_u64 v[216:217], s[10:11], 0, v[162:163]
	s_add_i32 m0, s64, 0xc000
	ds_read_b128 v[184:187], v182
	ds_read_b128 v[188:191], v182 offset:1024
	ds_read_b128 v[192:195], v182 offset:2048
	ds_read_b128 v[196:199], v182 offset:3072
	ds_read_b128 v[200:203], v182 offset:4096
	ds_read_b128 v[204:207], v182 offset:5120
	ds_read_b128 v[208:211], v182 offset:6144
	ds_read_b128 v[212:215], v182 offset:7168
	global_load_lds_dwordx4 v[216:217], off
	v_lshl_add_u64 v[216:217], s[10:11], 0, v[164:165]
	s_add_i32 m0, s64, 0xe000
	s_nop 0
	global_load_lds_dwordx4 v[216:217], off
	s_waitcnt vmcnt(8)
	s_waitcnt lgkmcnt(0)
	s_barrier
	s_setprio 1
	s_waitcnt lgkmcnt(0)
	v_mfma_f32_16x16x32_bf16 v[126:129], v[130:133], v[184:187], v[126:129]
	v_mfma_f32_16x16x32_bf16 v[122:125], v[138:141], v[184:187], v[122:125]
	v_mfma_f32_16x16x32_bf16 v[110:113], v[130:133], v[192:195], v[110:113]
	v_mfma_f32_16x16x32_bf16 v[106:109], v[138:141], v[192:195], v[106:109]
	v_mfma_f32_16x16x32_bf16 v[94:97], v[130:133], v[200:203], v[94:97]
	v_mfma_f32_16x16x32_bf16 v[90:93], v[138:141], v[200:203], v[90:93]
	v_mfma_f32_16x16x32_bf16 v[78:81], v[130:133], v[208:211], v[78:81]
	v_mfma_f32_16x16x32_bf16 v[74:77], v[138:141], v[208:211], v[74:77]
	v_mfma_f32_16x16x32_bf16 v[126:129], v[134:137], v[188:191], v[126:129]
	v_mfma_f32_16x16x32_bf16 v[122:125], v[142:145], v[188:191], v[122:125]
	v_mfma_f32_16x16x32_bf16 v[110:113], v[134:137], v[196:199], v[110:113]
	v_mfma_f32_16x16x32_bf16 v[106:109], v[142:145], v[196:199], v[106:109]
	v_mfma_f32_16x16x32_bf16 v[94:97], v[134:137], v[204:207], v[94:97]
	v_mfma_f32_16x16x32_bf16 v[90:93], v[142:145], v[204:207], v[90:93]
	v_mfma_f32_16x16x32_bf16 v[78:81], v[134:137], v[212:215], v[78:81]
	v_mfma_f32_16x16x32_bf16 v[74:77], v[142:145], v[212:215], v[74:77]
	s_setprio 0
	s_setprio 1
	v_mfma_f32_16x16x32_bf16 v[118:121], v[146:149], v[184:187], v[118:121]
	v_mfma_f32_16x16x32_bf16 v[114:117], v[170:173], v[184:187], v[114:117]
	v_mfma_f32_16x16x32_bf16 v[102:105], v[146:149], v[192:195], v[102:105]
	v_mfma_f32_16x16x32_bf16 v[98:101], v[170:173], v[192:195], v[98:101]
	v_mfma_f32_16x16x32_bf16 v[86:89], v[146:149], v[200:203], v[86:89]
	v_mfma_f32_16x16x32_bf16 v[82:85], v[170:173], v[200:203], v[82:85]
	v_mfma_f32_16x16x32_bf16 v[70:73], v[146:149], v[208:211], v[70:73]
	v_mfma_f32_16x16x32_bf16 v[66:69], v[170:173], v[208:211], v[66:69]
	v_mfma_f32_16x16x32_bf16 v[118:121], v[150:153], v[188:191], v[118:121]
	v_mfma_f32_16x16x32_bf16 v[114:117], v[174:177], v[188:191], v[114:117]
	v_mfma_f32_16x16x32_bf16 v[102:105], v[150:153], v[196:199], v[102:105]
	v_mfma_f32_16x16x32_bf16 v[98:101], v[174:177], v[196:199], v[98:101]
	v_mfma_f32_16x16x32_bf16 v[86:89], v[150:153], v[204:207], v[86:89]
	v_mfma_f32_16x16x32_bf16 v[82:85], v[174:177], v[204:207], v[82:85]
	v_mfma_f32_16x16x32_bf16 v[70:73], v[150:153], v[212:215], v[70:73]
	v_mfma_f32_16x16x32_bf16 v[66:69], v[174:177], v[212:215], v[66:69]
	s_setprio 0
	s_barrier
	s_add_i32 s84, s78, s63
	v_lshl_add_u64 v[216:217], s[44:45], 0, v[156:157]
	s_mov_b32 m0, s84
	ds_read_b128 v[184:187], v182 offset:16384
	ds_read_b128 v[188:191], v182 offset:17408
	ds_read_b128 v[192:195], v182 offset:18432
	ds_read_b128 v[196:199], v182 offset:19456
	ds_read_b128 v[200:203], v182 offset:20480
	ds_read_b128 v[204:207], v182 offset:21504
	ds_read_b128 v[208:211], v182 offset:22528
	ds_read_b128 v[212:215], v182 offset:23552
	global_load_lds_dwordx4 v[216:217], off
	s_add_i32 m0, s84, 0x2000
	s_add_u32 s84, s44, 0x40000
	v_lshl_add_u64 v[218:219], s[44:45], 0, v[160:161]
	s_addc_u32 s85, s45, 0
	s_add_i32 s86, s79, s63
	global_load_lds_dwordx4 v[218:219], off
	v_lshl_add_u64 v[220:221], s[84:85], 0, v[156:157]
	s_mov_b32 m0, s86
	v_lshl_add_u64 v[222:223], s[46:47], 0, v[158:159]
	global_load_lds_dwordx4 v[220:221], off
	v_lshl_add_u64 v[220:221], s[84:85], 0, v[160:161]
	s_add_i32 m0, s86, 0x2000
	s_nop 0
	global_load_lds_dwordx4 v[220:221], off
	v_lshl_add_u64 v[220:221], s[46:47], 0, v[154:155]
	s_mov_b32 m0, s64
	s_nop 0
	global_load_lds_dwordx4 v[220:221], off
	s_mov_b32 m0, s65
	s_nop 0
	global_load_lds_dwordx4 v[222:223], off
	s_waitcnt vmcnt(8)
	s_waitcnt lgkmcnt(0)
	s_barrier
	s_setprio 1
	s_waitcnt lgkmcnt(0)
	v_mfma_f32_16x16x32_bf16 v[62:65], v[130:133], v[184:187], v[62:65]
	v_mfma_f32_16x16x32_bf16 v[58:61], v[138:141], v[184:187], v[58:61]
	v_mfma_f32_16x16x32_bf16 v[46:49], v[130:133], v[192:195], v[46:49]
	v_mfma_f32_16x16x32_bf16 v[42:45], v[138:141], v[192:195], v[42:45]
	v_mfma_f32_16x16x32_bf16 v[30:33], v[130:133], v[200:203], v[30:33]
	v_mfma_f32_16x16x32_bf16 v[26:29], v[138:141], v[200:203], v[26:29]
	v_mfma_f32_16x16x32_bf16 v[14:17], v[130:133], v[208:211], v[14:17]
	v_mfma_f32_16x16x32_bf16 v[10:13], v[138:141], v[208:211], v[10:13]
	v_mfma_f32_16x16x32_bf16 v[62:65], v[134:137], v[188:191], v[62:65]
	v_mfma_f32_16x16x32_bf16 v[58:61], v[142:145], v[188:191], v[58:61]
	v_mfma_f32_16x16x32_bf16 v[46:49], v[134:137], v[196:199], v[46:49]
	v_mfma_f32_16x16x32_bf16 v[42:45], v[142:145], v[196:199], v[42:45]
	v_mfma_f32_16x16x32_bf16 v[30:33], v[134:137], v[204:207], v[30:33]
	v_mfma_f32_16x16x32_bf16 v[26:29], v[142:145], v[204:207], v[26:29]
	v_mfma_f32_16x16x32_bf16 v[14:17], v[134:137], v[212:215], v[14:17]
	v_mfma_f32_16x16x32_bf16 v[10:13], v[142:145], v[212:215], v[10:13]
	s_setprio 0
	s_setprio 1
	v_mfma_f32_16x16x32_bf16 v[54:57], v[146:149], v[184:187], v[54:57]
	v_mfma_f32_16x16x32_bf16 v[50:53], v[170:173], v[184:187], v[50:53]
	v_mfma_f32_16x16x32_bf16 v[38:41], v[146:149], v[192:195], v[38:41]
	v_mfma_f32_16x16x32_bf16 v[34:37], v[170:173], v[192:195], v[34:37]
	v_mfma_f32_16x16x32_bf16 v[22:25], v[146:149], v[200:203], v[22:25]
	v_mfma_f32_16x16x32_bf16 v[18:21], v[170:173], v[200:203], v[18:21]
	v_mfma_f32_16x16x32_bf16 v[6:9], v[146:149], v[208:211], v[6:9]
	v_mfma_f32_16x16x32_bf16 v[2:5], v[170:173], v[208:211], v[2:5]
	v_mfma_f32_16x16x32_bf16 v[54:57], v[150:153], v[188:191], v[54:57]
	v_mfma_f32_16x16x32_bf16 v[50:53], v[174:177], v[188:191], v[50:53]
	v_mfma_f32_16x16x32_bf16 v[38:41], v[150:153], v[196:199], v[38:41]
	v_mfma_f32_16x16x32_bf16 v[34:37], v[174:177], v[196:199], v[34:37]
	v_mfma_f32_16x16x32_bf16 v[22:25], v[150:153], v[204:207], v[22:25]
	v_mfma_f32_16x16x32_bf16 v[18:21], v[174:177], v[204:207], v[18:21]
	v_mfma_f32_16x16x32_bf16 v[6:9], v[150:153], v[212:215], v[6:9]
	v_mfma_f32_16x16x32_bf16 v[2:5], v[174:177], v[212:215], v[2:5]
	s_setprio 0
	s_barrier
	s_add_i32 s84, 0, 0x18000
	s_add_i32 s85, 0, 0x1c000
	v_add_u32_e32 v142, s84, v179
	v_add_u32_e32 v174, s85, v179
	ds_read_b128 v[130:133], v142
	ds_read_b128 v[134:137], v142 offset:1024
	ds_read_b128 v[138:141], v142 offset:2048
	ds_read_b128 v[142:145], v142 offset:3072
	ds_read_b128 v[146:149], v174
	ds_read_b128 v[150:153], v174 offset:1024
	ds_read_b128 v[170:173], v174 offset:2048
	ds_read_b128 v[174:177], v174 offset:3072
	s_add_u32 s46, s46, 0x40000
	s_addc_u32 s47, s47, 0
	s_mov_b32 m0, s66
	v_lshl_add_u64 v[224:225], s[46:47], 0, v[154:155]
	ds_read_b128 v[184:187], v182 offset:32768
	ds_read_b128 v[188:191], v182 offset:33792
	ds_read_b128 v[192:195], v182 offset:34816
	ds_read_b128 v[196:199], v182 offset:35840
	ds_read_b128 v[200:203], v182 offset:36864
	ds_read_b128 v[204:207], v182 offset:37888
	ds_read_b128 v[208:211], v182 offset:38912
	ds_read_b128 v[212:215], v182 offset:39936
	global_load_lds_dwordx4 v[224:225], off
	v_lshl_add_u64 v[224:225], s[46:47], 0, v[158:159]
	s_mov_b32 m0, s67
	s_nop 0
	global_load_lds_dwordx4 v[224:225], off
	s_waitcnt vmcnt(8)
	s_waitcnt lgkmcnt(0)
	s_barrier
	s_setprio 1
	s_waitcnt lgkmcnt(0)
	v_mfma_f32_16x16x32_bf16 v[126:129], v[130:133], v[184:187], v[126:129]
	v_mfma_f32_16x16x32_bf16 v[122:125], v[138:141], v[184:187], v[122:125]
	v_mfma_f32_16x16x32_bf16 v[110:113], v[130:133], v[192:195], v[110:113]
	v_mfma_f32_16x16x32_bf16 v[106:109], v[138:141], v[192:195], v[106:109]
	v_mfma_f32_16x16x32_bf16 v[94:97], v[130:133], v[200:203], v[94:97]
	v_mfma_f32_16x16x32_bf16 v[90:93], v[138:141], v[200:203], v[90:93]
	v_mfma_f32_16x16x32_bf16 v[78:81], v[130:133], v[208:211], v[78:81]
	v_mfma_f32_16x16x32_bf16 v[74:77], v[138:141], v[208:211], v[74:77]
	v_mfma_f32_16x16x32_bf16 v[126:129], v[134:137], v[188:191], v[126:129]
	v_mfma_f32_16x16x32_bf16 v[122:125], v[142:145], v[188:191], v[122:125]
	v_mfma_f32_16x16x32_bf16 v[110:113], v[134:137], v[196:199], v[110:113]
	v_mfma_f32_16x16x32_bf16 v[106:109], v[142:145], v[196:199], v[106:109]
	v_mfma_f32_16x16x32_bf16 v[94:97], v[134:137], v[204:207], v[94:97]
	v_mfma_f32_16x16x32_bf16 v[90:93], v[142:145], v[204:207], v[90:93]
	v_mfma_f32_16x16x32_bf16 v[78:81], v[134:137], v[212:215], v[78:81]
	v_mfma_f32_16x16x32_bf16 v[74:77], v[142:145], v[212:215], v[74:77]
	s_setprio 0
	s_setprio 1
	v_mfma_f32_16x16x32_bf16 v[118:121], v[146:149], v[184:187], v[118:121]
	v_mfma_f32_16x16x32_bf16 v[114:117], v[170:173], v[184:187], v[114:117]
	v_mfma_f32_16x16x32_bf16 v[102:105], v[146:149], v[192:195], v[102:105]
	v_mfma_f32_16x16x32_bf16 v[98:101], v[170:173], v[192:195], v[98:101]
	v_mfma_f32_16x16x32_bf16 v[86:89], v[146:149], v[200:203], v[86:89]
	v_mfma_f32_16x16x32_bf16 v[82:85], v[170:173], v[200:203], v[82:85]
	v_mfma_f32_16x16x32_bf16 v[70:73], v[146:149], v[208:211], v[70:73]
	v_mfma_f32_16x16x32_bf16 v[66:69], v[170:173], v[208:211], v[66:69]
	v_mfma_f32_16x16x32_bf16 v[118:121], v[150:153], v[188:191], v[118:121]
	v_mfma_f32_16x16x32_bf16 v[114:117], v[174:177], v[188:191], v[114:117]
	v_mfma_f32_16x16x32_bf16 v[102:105], v[150:153], v[196:199], v[102:105]
	v_mfma_f32_16x16x32_bf16 v[98:101], v[174:177], v[196:199], v[98:101]
	v_mfma_f32_16x16x32_bf16 v[86:89], v[150:153], v[204:207], v[86:89]
	v_mfma_f32_16x16x32_bf16 v[82:85], v[174:177], v[204:207], v[82:85]
	v_mfma_f32_16x16x32_bf16 v[70:73], v[150:153], v[212:215], v[70:73]
	v_mfma_f32_16x16x32_bf16 v[66:69], v[174:177], v[212:215], v[66:69]
	s_setprio 0
	s_barrier
	s_add_i32 s46, s84, s63
	v_lshl_add_u64 v[216:217], v[216:217], 0, s[14:15]
	s_mov_b32 m0, s46
	ds_read_b128 v[184:187], v182 offset:49152
	ds_read_b128 v[188:191], v182 offset:50176
	ds_read_b128 v[192:195], v182 offset:51200
	ds_read_b128 v[196:199], v182 offset:52224
	ds_read_b128 v[200:203], v182 offset:53248
	ds_read_b128 v[204:207], v182 offset:54272
	ds_read_b128 v[208:211], v182 offset:55296
	ds_read_b128 v[212:215], v182 offset:56320
	global_load_lds_dwordx4 v[216:217], off
	s_add_i32 m0, s46, 0x2000
	s_add_u32 s44, s44, 0x40080
	v_lshl_add_u64 v[216:217], v[218:219], 0, s[14:15]
	s_addc_u32 s45, s45, 0
	s_add_i32 s46, s85, s63
	global_load_lds_dwordx4 v[216:217], off
	v_lshl_add_u64 v[216:217], s[44:45], 0, v[156:157]
	s_mov_b32 m0, s46
	s_nop 0
	global_load_lds_dwordx4 v[216:217], off
	v_lshl_add_u64 v[216:217], s[44:45], 0, v[160:161]
	s_add_i32 m0, s46, 0x2000
	s_nop 0
	global_load_lds_dwordx4 v[216:217], off
	v_lshl_add_u64 v[216:217], v[220:221], 0, s[14:15]
	s_mov_b32 m0, s75
	s_nop 0
	global_load_lds_dwordx4 v[216:217], off
	v_lshl_add_u64 v[216:217], v[222:223], 0, s[14:15]
	s_mov_b32 m0, s76
	s_nop 0
	global_load_lds_dwordx4 v[216:217], off
	s_waitcnt vmcnt(8)
	s_waitcnt lgkmcnt(0)
	s_barrier
	s_setprio 1
	s_waitcnt lgkmcnt(0)
	v_mfma_f32_16x16x32_bf16 v[62:65], v[130:133], v[184:187], v[62:65]
	v_mfma_f32_16x16x32_bf16 v[58:61], v[138:141], v[184:187], v[58:61]
	v_mfma_f32_16x16x32_bf16 v[46:49], v[130:133], v[192:195], v[46:49]
	v_mfma_f32_16x16x32_bf16 v[42:45], v[138:141], v[192:195], v[42:45]
	v_mfma_f32_16x16x32_bf16 v[30:33], v[130:133], v[200:203], v[30:33]
	v_mfma_f32_16x16x32_bf16 v[26:29], v[138:141], v[200:203], v[26:29]
	v_mfma_f32_16x16x32_bf16 v[14:17], v[130:133], v[208:211], v[14:17]
	v_mfma_f32_16x16x32_bf16 v[10:13], v[138:141], v[208:211], v[10:13]
	v_mfma_f32_16x16x32_bf16 v[62:65], v[134:137], v[188:191], v[62:65]
	v_mfma_f32_16x16x32_bf16 v[58:61], v[142:145], v[188:191], v[58:61]
	v_mfma_f32_16x16x32_bf16 v[46:49], v[134:137], v[196:199], v[46:49]
	v_mfma_f32_16x16x32_bf16 v[42:45], v[142:145], v[196:199], v[42:45]
	v_mfma_f32_16x16x32_bf16 v[30:33], v[134:137], v[204:207], v[30:33]
	v_mfma_f32_16x16x32_bf16 v[26:29], v[142:145], v[204:207], v[26:29]
	v_mfma_f32_16x16x32_bf16 v[14:17], v[134:137], v[212:215], v[14:17]
	v_mfma_f32_16x16x32_bf16 v[10:13], v[142:145], v[212:215], v[10:13]
	s_setprio 0
	s_setprio 1
	v_mfma_f32_16x16x32_bf16 v[54:57], v[146:149], v[184:187], v[54:57]
	v_mfma_f32_16x16x32_bf16 v[50:53], v[170:173], v[184:187], v[50:53]
	v_mfma_f32_16x16x32_bf16 v[38:41], v[146:149], v[192:195], v[38:41]
	v_mfma_f32_16x16x32_bf16 v[34:37], v[170:173], v[192:195], v[34:37]
	v_mfma_f32_16x16x32_bf16 v[22:25], v[146:149], v[200:203], v[22:25]
	v_mfma_f32_16x16x32_bf16 v[18:21], v[170:173], v[200:203], v[18:21]
	v_mfma_f32_16x16x32_bf16 v[6:9], v[146:149], v[208:211], v[6:9]
	v_mfma_f32_16x16x32_bf16 v[2:5], v[170:173], v[208:211], v[2:5]
	v_mfma_f32_16x16x32_bf16 v[54:57], v[150:153], v[188:191], v[54:57]
	v_mfma_f32_16x16x32_bf16 v[50:53], v[174:177], v[188:191], v[50:53]
	v_mfma_f32_16x16x32_bf16 v[38:41], v[150:153], v[196:199], v[38:41]
	v_mfma_f32_16x16x32_bf16 v[34:37], v[174:177], v[196:199], v[34:37]
	v_mfma_f32_16x16x32_bf16 v[22:25], v[150:153], v[204:207], v[22:25]
	v_mfma_f32_16x16x32_bf16 v[18:21], v[174:177], v[204:207], v[18:21]
	v_mfma_f32_16x16x32_bf16 v[6:9], v[150:153], v[212:215], v[6:9]
	v_mfma_f32_16x16x32_bf16 v[2:5], v[174:177], v[212:215], v[2:5]
	s_setprio 0
	s_add_i32 s83, s83, 2
	s_add_u32 s10, s10, 0x100
	s_addc_u32 s11, s11, 0
	s_add_u32 s81, s81, 0x100
	s_addc_u32 s82, s82, 0
	s_cmp_gt_u32 s83, 13
	s_barrier
	s_cbranch_scc0 .LBB0_726
	s_and_b64 vcc, exec, s[22:23]
	s_cbranch_vccz .LBB0_729
	s_barrier

.LBB0_807:
	ds_read_b128 v[130:133], v172
	ds_read_b128 v[134:137], v172 offset:1024
	ds_read_b128 v[138:141], v172 offset:2048
	ds_read_b128 v[142:145], v172 offset:3072
	ds_read_b128 v[162:165], v173
	ds_read_b128 v[166:169], v173 offset:1024
	ds_read_b128 v[176:179], v173 offset:2048
	ds_read_b128 v[180:183], v173 offset:3072
	s_add_u32 s46, s44, 0xfff80080
	s_addc_u32 s47, s45, -1
	s_cmp_eq_u32 s84, 28
	s_cselect_b32 s49, s27, s47
	s_cselect_b32 s48, s43, s46
	s_cselect_b32 s47, s25, s83
	s_cselect_b32 s46, s72, s73
	v_lshl_add_u64 v[216:217], s[44:45], 0, v[154:155]
	s_add_i32 m0, s65, 0xc000
	ds_read_b128 v[184:187], v174
	ds_read_b128 v[188:191], v174 offset:1024
	ds_read_b128 v[192:195], v174 offset:2048
	ds_read_b128 v[196:199], v174 offset:3072
	ds_read_b128 v[200:203], v174 offset:4096
	ds_read_b128 v[204:207], v174 offset:5120
	ds_read_b128 v[208:211], v174 offset:6144
	ds_read_b128 v[212:215], v174 offset:7168
	global_load_lds_dwordx4 v[216:217], off
	v_lshl_add_u64 v[216:217], s[44:45], 0, v[156:157]
	s_add_i32 m0, s65, 0xe000
	s_nop 0
	global_load_lds_dwordx4 v[216:217], off
	s_waitcnt vmcnt(8)
	s_waitcnt lgkmcnt(0)
	s_barrier
	s_setprio 1
	s_waitcnt lgkmcnt(0)
	v_mfma_f32_16x16x32_bf16 v[126:129], v[130:133], v[184:187], v[126:129]
	v_mfma_f32_16x16x32_bf16 v[122:125], v[138:141], v[184:187], v[122:125]
	v_mfma_f32_16x16x32_bf16 v[110:113], v[130:133], v[192:195], v[110:113]
	v_mfma_f32_16x16x32_bf16 v[106:109], v[138:141], v[192:195], v[106:109]
	v_mfma_f32_16x16x32_bf16 v[94:97], v[130:133], v[200:203], v[94:97]
	v_mfma_f32_16x16x32_bf16 v[90:93], v[138:141], v[200:203], v[90:93]
	v_mfma_f32_16x16x32_bf16 v[78:81], v[130:133], v[208:211], v[78:81]
	v_mfma_f32_16x16x32_bf16 v[74:77], v[138:141], v[208:211], v[74:77]
	v_mfma_f32_16x16x32_bf16 v[126:129], v[134:137], v[188:191], v[126:129]
	v_mfma_f32_16x16x32_bf16 v[122:125], v[142:145], v[188:191], v[122:125]
	v_mfma_f32_16x16x32_bf16 v[110:113], v[134:137], v[196:199], v[110:113]
	v_mfma_f32_16x16x32_bf16 v[106:109], v[142:145], v[196:199], v[106:109]
	v_mfma_f32_16x16x32_bf16 v[94:97], v[134:137], v[204:207], v[94:97]
	v_mfma_f32_16x16x32_bf16 v[90:93], v[142:145], v[204:207], v[90:93]
	v_mfma_f32_16x16x32_bf16 v[78:81], v[134:137], v[212:215], v[78:81]
	v_mfma_f32_16x16x32_bf16 v[74:77], v[142:145], v[212:215], v[74:77]
	s_setprio 0
	s_setprio 1
	v_mfma_f32_16x16x32_bf16 v[118:121], v[162:165], v[184:187], v[118:121]
	v_mfma_f32_16x16x32_bf16 v[114:117], v[176:179], v[184:187], v[114:117]
	v_mfma_f32_16x16x32_bf16 v[102:105], v[162:165], v[192:195], v[102:105]
	v_mfma_f32_16x16x32_bf16 v[98:101], v[176:179], v[192:195], v[98:101]
	v_mfma_f32_16x16x32_bf16 v[86:89], v[162:165], v[200:203], v[86:89]
	v_mfma_f32_16x16x32_bf16 v[82:85], v[176:179], v[200:203], v[82:85]
	v_mfma_f32_16x16x32_bf16 v[70:73], v[162:165], v[208:211], v[70:73]
	v_mfma_f32_16x16x32_bf16 v[66:69], v[176:179], v[208:211], v[66:69]
	v_mfma_f32_16x16x32_bf16 v[118:121], v[166:169], v[188:191], v[118:121]
	v_mfma_f32_16x16x32_bf16 v[114:117], v[180:183], v[188:191], v[114:117]
	v_mfma_f32_16x16x32_bf16 v[102:105], v[166:169], v[196:199], v[102:105]
	v_mfma_f32_16x16x32_bf16 v[98:101], v[180:183], v[196:199], v[98:101]
	v_mfma_f32_16x16x32_bf16 v[86:89], v[166:169], v[204:207], v[86:89]
	v_mfma_f32_16x16x32_bf16 v[82:85], v[180:183], v[204:207], v[82:85]
	v_mfma_f32_16x16x32_bf16 v[70:73], v[166:169], v[212:215], v[70:73]
	v_mfma_f32_16x16x32_bf16 v[66:69], v[180:183], v[212:215], v[66:69]
	s_setprio 0
	s_barrier
	s_add_i32 s85, s80, s64
	v_lshl_add_u64 v[216:217], s[46:47], 0, v[148:149]
	s_mov_b32 m0, s85
	ds_read_b128 v[184:187], v174 offset:16384
	ds_read_b128 v[188:191], v174 offset:17408
	ds_read_b128 v[192:195], v174 offset:18432
	ds_read_b128 v[196:199], v174 offset:19456
	ds_read_b128 v[200:203], v174 offset:20480
	ds_read_b128 v[204:207], v174 offset:21504
	ds_read_b128 v[208:211], v174 offset:22528
	ds_read_b128 v[212:215], v174 offset:23552
	global_load_lds_dwordx4 v[216:217], off
	s_add_i32 m0, s85, 0x2000
	s_add_u32 s86, s46, 0x80000
	v_lshl_add_u64 v[218:219], s[46:47], 0, v[152:153]
	s_addc_u32 s87, s47, 0
	s_add_i32 s85, s81, s64
	global_load_lds_dwordx4 v[218:219], off
	v_lshl_add_u64 v[220:221], s[86:87], 0, v[148:149]
	s_mov_b32 m0, s85
	v_lshl_add_u64 v[222:223], s[48:49], 0, v[150:151]
	global_load_lds_dwordx4 v[220:221], off
	v_lshl_add_u64 v[220:221], s[86:87], 0, v[152:153]
	s_add_i32 m0, s85, 0x2000
	s_nop 0
	global_load_lds_dwordx4 v[220:221], off
	v_lshl_add_u64 v[220:221], s[48:49], 0, v[146:147]
	s_mov_b32 m0, s65
	s_nop 0
	global_load_lds_dwordx4 v[220:221], off
	s_mov_b32 m0, s66
	s_nop 0
	global_load_lds_dwordx4 v[222:223], off
	s_waitcnt vmcnt(8)
	s_waitcnt lgkmcnt(0)
	s_barrier
	s_setprio 1
	s_waitcnt lgkmcnt(0)
	v_mfma_f32_16x16x32_bf16 v[62:65], v[130:133], v[184:187], v[62:65]
	v_mfma_f32_16x16x32_bf16 v[58:61], v[138:141], v[184:187], v[58:61]
	v_mfma_f32_16x16x32_bf16 v[46:49], v[130:133], v[192:195], v[46:49]
	v_mfma_f32_16x16x32_bf16 v[42:45], v[138:141], v[192:195], v[42:45]
	v_mfma_f32_16x16x32_bf16 v[30:33], v[130:133], v[200:203], v[30:33]
	v_mfma_f32_16x16x32_bf16 v[26:29], v[138:141], v[200:203], v[26:29]
	v_mfma_f32_16x16x32_bf16 v[14:17], v[130:133], v[208:211], v[14:17]
	v_mfma_f32_16x16x32_bf16 v[10:13], v[138:141], v[208:211], v[10:13]
	v_mfma_f32_16x16x32_bf16 v[62:65], v[134:137], v[188:191], v[62:65]
	v_mfma_f32_16x16x32_bf16 v[58:61], v[142:145], v[188:191], v[58:61]
	v_mfma_f32_16x16x32_bf16 v[46:49], v[134:137], v[196:199], v[46:49]
	v_mfma_f32_16x16x32_bf16 v[42:45], v[142:145], v[196:199], v[42:45]
	v_mfma_f32_16x16x32_bf16 v[30:33], v[134:137], v[204:207], v[30:33]
	v_mfma_f32_16x16x32_bf16 v[26:29], v[142:145], v[204:207], v[26:29]
	v_mfma_f32_16x16x32_bf16 v[14:17], v[134:137], v[212:215], v[14:17]
	v_mfma_f32_16x16x32_bf16 v[10:13], v[142:145], v[212:215], v[10:13]
	s_setprio 0
	s_setprio 1
	v_mfma_f32_16x16x32_bf16 v[54:57], v[162:165], v[184:187], v[54:57]
	v_mfma_f32_16x16x32_bf16 v[50:53], v[176:179], v[184:187], v[50:53]
	v_mfma_f32_16x16x32_bf16 v[38:41], v[162:165], v[192:195], v[38:41]
	v_mfma_f32_16x16x32_bf16 v[34:37], v[176:179], v[192:195], v[34:37]
	v_mfma_f32_16x16x32_bf16 v[22:25], v[162:165], v[200:203], v[22:25]
	v_mfma_f32_16x16x32_bf16 v[18:21], v[176:179], v[200:203], v[18:21]
	v_mfma_f32_16x16x32_bf16 v[6:9], v[162:165], v[208:211], v[6:9]
	v_mfma_f32_16x16x32_bf16 v[2:5], v[176:179], v[208:211], v[2:5]
	v_mfma_f32_16x16x32_bf16 v[54:57], v[166:169], v[188:191], v[54:57]
	v_mfma_f32_16x16x32_bf16 v[50:53], v[180:183], v[188:191], v[50:53]
	v_mfma_f32_16x16x32_bf16 v[38:41], v[166:169], v[196:199], v[38:41]
	v_mfma_f32_16x16x32_bf16 v[34:37], v[180:183], v[196:199], v[34:37]
	v_mfma_f32_16x16x32_bf16 v[22:25], v[166:169], v[204:207], v[22:25]
	v_mfma_f32_16x16x32_bf16 v[18:21], v[180:183], v[204:207], v[18:21]
	v_mfma_f32_16x16x32_bf16 v[6:9], v[166:169], v[212:215], v[6:9]
	v_mfma_f32_16x16x32_bf16 v[2:5], v[180:183], v[212:215], v[2:5]
	s_setprio 0
	s_barrier
	s_add_i32 s85, 0, 0x18000
	s_add_i32 s86, 0, 0x1c000
	v_add_u32_e32 v142, s85, v170
	v_add_u32_e32 v180, s86, v170
	ds_read_b128 v[130:133], v142
	ds_read_b128 v[134:137], v142 offset:1024
	ds_read_b128 v[138:141], v142 offset:2048
	ds_read_b128 v[142:145], v142 offset:3072
	ds_read_b128 v[162:165], v180
	ds_read_b128 v[166:169], v180 offset:1024
	ds_read_b128 v[176:179], v180 offset:2048
	ds_read_b128 v[180:183], v180 offset:3072
	s_add_u32 s48, s48, 0x80000
	s_addc_u32 s49, s49, 0
	s_mov_b32 m0, s67
	v_lshl_add_u64 v[224:225], s[48:49], 0, v[146:147]
	ds_read_b128 v[184:187], v174 offset:32768
	ds_read_b128 v[188:191], v174 offset:33792
	ds_read_b128 v[192:195], v174 offset:34816
	ds_read_b128 v[196:199], v174 offset:35840
	ds_read_b128 v[200:203], v174 offset:36864
	ds_read_b128 v[204:207], v174 offset:37888
	ds_read_b128 v[208:211], v174 offset:38912
	ds_read_b128 v[212:215], v174 offset:39936
	global_load_lds_dwordx4 v[224:225], off
	v_lshl_add_u64 v[224:225], s[48:49], 0, v[150:151]
	s_mov_b32 m0, s74
	s_nop 0
	global_load_lds_dwordx4 v[224:225], off
	s_waitcnt vmcnt(8)
	s_waitcnt lgkmcnt(0)
	s_barrier
	s_setprio 1
	s_waitcnt lgkmcnt(0)
	v_mfma_f32_16x16x32_bf16 v[126:129], v[130:133], v[184:187], v[126:129]
	v_mfma_f32_16x16x32_bf16 v[122:125], v[138:141], v[184:187], v[122:125]
	v_mfma_f32_16x16x32_bf16 v[110:113], v[130:133], v[192:195], v[110:113]
	v_mfma_f32_16x16x32_bf16 v[106:109], v[138:141], v[192:195], v[106:109]
	v_mfma_f32_16x16x32_bf16 v[94:97], v[130:133], v[200:203], v[94:97]
	v_mfma_f32_16x16x32_bf16 v[90:93], v[138:141], v[200:203], v[90:93]
	v_mfma_f32_16x16x32_bf16 v[78:81], v[130:133], v[208:211], v[78:81]
	v_mfma_f32_16x16x32_bf16 v[74:77], v[138:141], v[208:211], v[74:77]
	v_mfma_f32_16x16x32_bf16 v[126:129], v[134:137], v[188:191], v[126:129]
	v_mfma_f32_16x16x32_bf16 v[122:125], v[142:145], v[188:191], v[122:125]
	v_mfma_f32_16x16x32_bf16 v[110:113], v[134:137], v[196:199], v[110:113]
	v_mfma_f32_16x16x32_bf16 v[106:109], v[142:145], v[196:199], v[106:109]
	v_mfma_f32_16x16x32_bf16 v[94:97], v[134:137], v[204:207], v[94:97]
	v_mfma_f32_16x16x32_bf16 v[90:93], v[142:145], v[204:207], v[90:93]
	v_mfma_f32_16x16x32_bf16 v[78:81], v[134:137], v[212:215], v[78:81]
	v_mfma_f32_16x16x32_bf16 v[74:77], v[142:145], v[212:215], v[74:77]
	s_setprio 0
	s_setprio 1
	v_mfma_f32_16x16x32_bf16 v[118:121], v[162:165], v[184:187], v[118:121]
	v_mfma_f32_16x16x32_bf16 v[114:117], v[176:179], v[184:187], v[114:117]
	v_mfma_f32_16x16x32_bf16 v[102:105], v[162:165], v[192:195], v[102:105]
	v_mfma_f32_16x16x32_bf16 v[98:101], v[176:179], v[192:195], v[98:101]
	v_mfma_f32_16x16x32_bf16 v[86:89], v[162:165], v[200:203], v[86:89]
	v_mfma_f32_16x16x32_bf16 v[82:85], v[176:179], v[200:203], v[82:85]
	v_mfma_f32_16x16x32_bf16 v[70:73], v[162:165], v[208:211], v[70:73]
	v_mfma_f32_16x16x32_bf16 v[66:69], v[176:179], v[208:211], v[66:69]
	v_mfma_f32_16x16x32_bf16 v[118:121], v[166:169], v[188:191], v[118:121]
	v_mfma_f32_16x16x32_bf16 v[114:117], v[180:183], v[188:191], v[114:117]
	v_mfma_f32_16x16x32_bf16 v[102:105], v[166:169], v[196:199], v[102:105]
	v_mfma_f32_16x16x32_bf16 v[98:101], v[180:183], v[196:199], v[98:101]
	v_mfma_f32_16x16x32_bf16 v[86:89], v[166:169], v[204:207], v[86:89]
	v_mfma_f32_16x16x32_bf16 v[82:85], v[180:183], v[204:207], v[82:85]
	v_mfma_f32_16x16x32_bf16 v[70:73], v[166:169], v[212:215], v[70:73]
	v_mfma_f32_16x16x32_bf16 v[66:69], v[180:183], v[212:215], v[66:69]
	s_setprio 0
	s_barrier
	s_add_i32 s48, s85, s64
	v_lshl_add_u64 v[216:217], v[216:217], 0, s[20:21]
	s_mov_b32 m0, s48
	ds_read_b128 v[184:187], v174 offset:49152
	ds_read_b128 v[188:191], v174 offset:50176
	ds_read_b128 v[192:195], v174 offset:51200
	ds_read_b128 v[196:199], v174 offset:52224
	ds_read_b128 v[200:203], v174 offset:53248
	ds_read_b128 v[204:207], v174 offset:54272
	ds_read_b128 v[208:211], v174 offset:55296
	ds_read_b128 v[212:215], v174 offset:56320
	global_load_lds_dwordx4 v[216:217], off
	s_add_i32 m0, s48, 0x2000
	s_add_u32 s46, s46, 0x80080
	v_lshl_add_u64 v[216:217], v[218:219], 0, s[20:21]
	s_addc_u32 s47, s47, 0
	s_add_i32 s48, s86, s64
	global_load_lds_dwordx4 v[216:217], off
	v_lshl_add_u64 v[216:217], s[46:47], 0, v[148:149]
	s_mov_b32 m0, s48
	s_nop 0
	global_load_lds_dwordx4 v[216:217], off
	v_lshl_add_u64 v[216:217], s[46:47], 0, v[152:153]
	s_add_i32 m0, s48, 0x2000
	s_nop 0
	global_load_lds_dwordx4 v[216:217], off
	v_lshl_add_u64 v[216:217], v[220:221], 0, s[20:21]
	s_mov_b32 m0, s76
	s_nop 0
	global_load_lds_dwordx4 v[216:217], off
	v_lshl_add_u64 v[216:217], v[222:223], 0, s[20:21]
	s_mov_b32 m0, s77
	s_nop 0
	global_load_lds_dwordx4 v[216:217], off
	s_waitcnt vmcnt(8)
	s_waitcnt lgkmcnt(0)
	s_barrier
	s_setprio 1
	s_waitcnt lgkmcnt(0)
	v_mfma_f32_16x16x32_bf16 v[62:65], v[130:133], v[184:187], v[62:65]
	v_mfma_f32_16x16x32_bf16 v[58:61], v[138:141], v[184:187], v[58:61]
	v_mfma_f32_16x16x32_bf16 v[46:49], v[130:133], v[192:195], v[46:49]
	v_mfma_f32_16x16x32_bf16 v[42:45], v[138:141], v[192:195], v[42:45]
	v_mfma_f32_16x16x32_bf16 v[30:33], v[130:133], v[200:203], v[30:33]
	v_mfma_f32_16x16x32_bf16 v[26:29], v[138:141], v[200:203], v[26:29]
	v_mfma_f32_16x16x32_bf16 v[14:17], v[130:133], v[208:211], v[14:17]
	v_mfma_f32_16x16x32_bf16 v[10:13], v[138:141], v[208:211], v[10:13]
	v_mfma_f32_16x16x32_bf16 v[62:65], v[134:137], v[188:191], v[62:65]
	v_mfma_f32_16x16x32_bf16 v[58:61], v[142:145], v[188:191], v[58:61]
	v_mfma_f32_16x16x32_bf16 v[46:49], v[134:137], v[196:199], v[46:49]
	v_mfma_f32_16x16x32_bf16 v[42:45], v[142:145], v[196:199], v[42:45]
	v_mfma_f32_16x16x32_bf16 v[30:33], v[134:137], v[204:207], v[30:33]
	v_mfma_f32_16x16x32_bf16 v[26:29], v[142:145], v[204:207], v[26:29]
	v_mfma_f32_16x16x32_bf16 v[14:17], v[134:137], v[212:215], v[14:17]
	v_mfma_f32_16x16x32_bf16 v[10:13], v[142:145], v[212:215], v[10:13]
	s_setprio 0
	s_setprio 1
	v_mfma_f32_16x16x32_bf16 v[54:57], v[162:165], v[184:187], v[54:57]
	v_mfma_f32_16x16x32_bf16 v[50:53], v[176:179], v[184:187], v[50:53]
	v_mfma_f32_16x16x32_bf16 v[38:41], v[162:165], v[192:195], v[38:41]
	v_mfma_f32_16x16x32_bf16 v[34:37], v[176:179], v[192:195], v[34:37]
	v_mfma_f32_16x16x32_bf16 v[22:25], v[162:165], v[200:203], v[22:25]
	v_mfma_f32_16x16x32_bf16 v[18:21], v[176:179], v[200:203], v[18:21]
	v_mfma_f32_16x16x32_bf16 v[6:9], v[162:165], v[208:211], v[6:9]
	v_mfma_f32_16x16x32_bf16 v[2:5], v[176:179], v[208:211], v[2:5]
	v_mfma_f32_16x16x32_bf16 v[54:57], v[166:169], v[188:191], v[54:57]
	v_mfma_f32_16x16x32_bf16 v[50:53], v[180:183], v[188:191], v[50:53]
	v_mfma_f32_16x16x32_bf16 v[38:41], v[166:169], v[196:199], v[38:41]
	v_mfma_f32_16x16x32_bf16 v[34:37], v[180:183], v[196:199], v[34:37]
	v_mfma_f32_16x16x32_bf16 v[22:25], v[166:169], v[204:207], v[22:25]
	v_mfma_f32_16x16x32_bf16 v[18:21], v[180:183], v[204:207], v[18:21]
	v_mfma_f32_16x16x32_bf16 v[6:9], v[166:169], v[212:215], v[6:9]
	v_mfma_f32_16x16x32_bf16 v[2:5], v[180:183], v[212:215], v[2:5]
	s_setprio 0
	s_add_i32 s84, s84, 2
	s_add_u32 s44, s44, 0x100
	s_addc_u32 s45, s45, 0
	s_add_u32 s73, s73, 0x100
	s_addc_u32 s83, s83, 0
	s_cmp_gt_u32 s84, 29
	s_barrier
	s_cbranch_scc0 .LBB0_807
	s_and_b64 vcc, exec, s[22:23]
	s_cbranch_vccz .LBB0_810
	s_barrier

.LBB0_894:
	ds_read_b128 v[130:133], v185
	ds_read_b128 v[134:137], v185 offset:1024
	ds_read_b128 v[138:141], v185 offset:2048
	ds_read_b128 v[142:145], v185 offset:3072
	ds_read_b128 v[164:167], v186
	ds_read_b128 v[168:171], v186 offset:1024
	ds_read_b128 v[172:175], v186 offset:2048
	ds_read_b128 v[176:179], v186 offset:3072
	s_add_u32 s44, s10, 0xfff80080
	s_addc_u32 s45, s11, -1
	s_cmp_eq_u32 s81, 28
	s_cselect_b32 s47, s9, s45
	s_cselect_b32 s46, s31, s44
	s_cselect_b32 s45, s29, s80
	s_cselect_b32 s44, s72, s73
	v_lshl_add_u64 v[180:181], s[10:11], 0, v[156:157]
	s_add_i32 m0, s61, 0xc000
	ds_read_b128 v[190:193], v187
	ds_read_b128 v[194:197], v187 offset:1024
	ds_read_b128 v[198:201], v187 offset:2048
	ds_read_b128 v[202:205], v187 offset:3072
	ds_read_b128 v[206:209], v187 offset:4096
	ds_read_b128 v[210:213], v187 offset:5120
	ds_read_b128 v[214:217], v187 offset:6144
	ds_read_b128 v[218:221], v187 offset:7168
	global_load_lds_dwordx4 v[180:181], off
	v_lshl_add_u64 v[180:181], s[10:11], 0, v[158:159]
	s_add_i32 m0, s61, 0xe000
	s_nop 0
	global_load_lds_dwordx4 v[180:181], off
	s_waitcnt vmcnt(8)
	s_waitcnt lgkmcnt(0)
	s_barrier
	s_setprio 1
	s_waitcnt lgkmcnt(0)
	v_mfma_f32_16x16x32_bf16 v[126:129], v[130:133], v[190:193], v[126:129]
	v_mfma_f32_16x16x32_bf16 v[122:125], v[138:141], v[190:193], v[122:125]
	v_mfma_f32_16x16x32_bf16 v[118:121], v[130:133], v[198:201], v[118:121]
	v_mfma_f32_16x16x32_bf16 v[110:113], v[138:141], v[198:201], v[110:113]
	v_mfma_f32_16x16x32_bf16 v[102:105], v[130:133], v[206:209], v[102:105]
	v_mfma_f32_16x16x32_bf16 v[94:97], v[138:141], v[206:209], v[94:97]
	v_mfma_f32_16x16x32_bf16 v[86:89], v[130:133], v[214:217], v[86:89]
	v_mfma_f32_16x16x32_bf16 v[78:81], v[138:141], v[214:217], v[78:81]
	v_mfma_f32_16x16x32_bf16 v[126:129], v[134:137], v[194:197], v[126:129]
	v_mfma_f32_16x16x32_bf16 v[122:125], v[142:145], v[194:197], v[122:125]
	v_mfma_f32_16x16x32_bf16 v[118:121], v[134:137], v[202:205], v[118:121]
	v_mfma_f32_16x16x32_bf16 v[110:113], v[142:145], v[202:205], v[110:113]
	v_mfma_f32_16x16x32_bf16 v[102:105], v[134:137], v[210:213], v[102:105]
	v_mfma_f32_16x16x32_bf16 v[94:97], v[142:145], v[210:213], v[94:97]
	v_mfma_f32_16x16x32_bf16 v[86:89], v[134:137], v[218:221], v[86:89]
	v_mfma_f32_16x16x32_bf16 v[78:81], v[142:145], v[218:221], v[78:81]
	s_setprio 0
	s_setprio 1
	v_mfma_f32_16x16x32_bf16 v[114:117], v[164:167], v[190:193], v[114:117]
	v_mfma_f32_16x16x32_bf16 v[106:109], v[172:175], v[190:193], v[106:109]
	v_mfma_f32_16x16x32_bf16 v[98:101], v[164:167], v[198:201], v[98:101]
	v_mfma_f32_16x16x32_bf16 v[90:93], v[172:175], v[198:201], v[90:93]
	v_mfma_f32_16x16x32_bf16 v[82:85], v[164:167], v[206:209], v[82:85]
	v_mfma_f32_16x16x32_bf16 v[74:77], v[172:175], v[206:209], v[74:77]
	v_mfma_f32_16x16x32_bf16 v[70:73], v[164:167], v[214:217], v[70:73]
	v_mfma_f32_16x16x32_bf16 v[66:69], v[172:175], v[214:217], v[66:69]
	v_mfma_f32_16x16x32_bf16 v[114:117], v[168:171], v[194:197], v[114:117]
	v_mfma_f32_16x16x32_bf16 v[106:109], v[176:179], v[194:197], v[106:109]
	v_mfma_f32_16x16x32_bf16 v[98:101], v[168:171], v[202:205], v[98:101]
	v_mfma_f32_16x16x32_bf16 v[90:93], v[176:179], v[202:205], v[90:93]
	v_mfma_f32_16x16x32_bf16 v[82:85], v[168:171], v[210:213], v[82:85]
	v_mfma_f32_16x16x32_bf16 v[74:77], v[176:179], v[210:213], v[74:77]
	v_mfma_f32_16x16x32_bf16 v[70:73], v[168:171], v[218:221], v[70:73]
	v_mfma_f32_16x16x32_bf16 v[66:69], v[176:179], v[218:221], v[66:69]
	s_setprio 0
	s_barrier
	s_add_i32 s82, s75, s48
	v_lshl_add_u64 v[180:181], s[44:45], 0, v[150:151]
	s_mov_b32 m0, s82
	ds_read_b128 v[190:193], v187 offset:16384
	ds_read_b128 v[194:197], v187 offset:17408
	ds_read_b128 v[198:201], v187 offset:18432
	ds_read_b128 v[202:205], v187 offset:19456
	ds_read_b128 v[206:209], v187 offset:20480
	ds_read_b128 v[210:213], v187 offset:21504
	ds_read_b128 v[214:217], v187 offset:22528
	ds_read_b128 v[218:221], v187 offset:23552
	global_load_lds_dwordx4 v[180:181], off
	s_add_i32 m0, s82, 0x2000
	s_add_u32 s82, s44, 0x80000
	v_lshl_add_u64 v[222:223], s[44:45], 0, v[146:147]
	s_addc_u32 s83, s45, 0
	s_add_i32 s84, s76, s48
	global_load_lds_dwordx4 v[222:223], off
	v_lshl_add_u64 v[224:225], s[82:83], 0, v[150:151]
	s_mov_b32 m0, s84
	v_lshl_add_u64 v[226:227], s[46:47], 0, v[148:149]
	global_load_lds_dwordx4 v[224:225], off
	v_lshl_add_u64 v[224:225], s[82:83], 0, v[146:147]
	s_add_i32 m0, s84, 0x2000
	s_nop 0
	global_load_lds_dwordx4 v[224:225], off
	v_lshl_add_u64 v[224:225], s[46:47], 0, v[152:153]
	s_mov_b32 m0, s61
	s_nop 0
	global_load_lds_dwordx4 v[224:225], off
	s_mov_b32 m0, s62
	s_nop 0
	global_load_lds_dwordx4 v[226:227], off
	s_waitcnt vmcnt(8)
	s_waitcnt lgkmcnt(0)
	s_barrier
	s_setprio 1
	s_waitcnt lgkmcnt(0)
	v_mfma_f32_16x16x32_bf16 v[62:65], v[130:133], v[190:193], v[62:65]
	v_mfma_f32_16x16x32_bf16 v[58:61], v[138:141], v[190:193], v[58:61]
	v_mfma_f32_16x16x32_bf16 v[54:57], v[130:133], v[198:201], v[54:57]
	v_mfma_f32_16x16x32_bf16 v[46:49], v[138:141], v[198:201], v[46:49]
	v_mfma_f32_16x16x32_bf16 v[38:41], v[130:133], v[206:209], v[38:41]
	v_mfma_f32_16x16x32_bf16 v[30:33], v[138:141], v[206:209], v[30:33]
	v_mfma_f32_16x16x32_bf16 v[22:25], v[130:133], v[214:217], v[22:25]
	v_mfma_f32_16x16x32_bf16 v[14:17], v[138:141], v[214:217], v[14:17]
	v_mfma_f32_16x16x32_bf16 v[62:65], v[134:137], v[194:197], v[62:65]
	v_mfma_f32_16x16x32_bf16 v[58:61], v[142:145], v[194:197], v[58:61]
	v_mfma_f32_16x16x32_bf16 v[54:57], v[134:137], v[202:205], v[54:57]
	v_mfma_f32_16x16x32_bf16 v[46:49], v[142:145], v[202:205], v[46:49]
	v_mfma_f32_16x16x32_bf16 v[38:41], v[134:137], v[210:213], v[38:41]
	v_mfma_f32_16x16x32_bf16 v[30:33], v[142:145], v[210:213], v[30:33]
	v_mfma_f32_16x16x32_bf16 v[22:25], v[134:137], v[218:221], v[22:25]
	v_mfma_f32_16x16x32_bf16 v[14:17], v[142:145], v[218:221], v[14:17]
	s_setprio 0
	s_setprio 1
	v_mfma_f32_16x16x32_bf16 v[50:53], v[164:167], v[190:193], v[50:53]
	v_mfma_f32_16x16x32_bf16 v[42:45], v[172:175], v[190:193], v[42:45]
	v_mfma_f32_16x16x32_bf16 v[34:37], v[164:167], v[198:201], v[34:37]
	v_mfma_f32_16x16x32_bf16 v[26:29], v[172:175], v[198:201], v[26:29]
	v_mfma_f32_16x16x32_bf16 v[18:21], v[164:167], v[206:209], v[18:21]
	v_mfma_f32_16x16x32_bf16 v[10:13], v[172:175], v[206:209], v[10:13]
	v_mfma_f32_16x16x32_bf16 v[6:9], v[164:167], v[214:217], v[6:9]
	v_mfma_f32_16x16x32_bf16 v[2:5], v[172:175], v[214:217], v[2:5]
	v_mfma_f32_16x16x32_bf16 v[50:53], v[168:171], v[194:197], v[50:53]
	v_mfma_f32_16x16x32_bf16 v[42:45], v[176:179], v[194:197], v[42:45]
	v_mfma_f32_16x16x32_bf16 v[34:37], v[168:171], v[202:205], v[34:37]
	v_mfma_f32_16x16x32_bf16 v[26:29], v[176:179], v[202:205], v[26:29]
	v_mfma_f32_16x16x32_bf16 v[18:21], v[168:171], v[210:213], v[18:21]
	v_mfma_f32_16x16x32_bf16 v[10:13], v[176:179], v[210:213], v[10:13]
	v_mfma_f32_16x16x32_bf16 v[6:9], v[168:171], v[218:221], v[6:9]
	v_mfma_f32_16x16x32_bf16 v[2:5], v[176:179], v[218:221], v[2:5]
	s_setprio 0
	s_barrier
	s_add_i32 s82, 0, 0x18000
	s_add_i32 s83, 0, 0x1c000
	v_add_u32_e32 v142, s82, v183
	v_add_u32_e32 v176, s83, v183
	ds_read_b128 v[130:133], v142
	ds_read_b128 v[134:137], v142 offset:1024
	ds_read_b128 v[138:141], v142 offset:2048
	ds_read_b128 v[142:145], v142 offset:3072
	ds_read_b128 v[164:167], v176
	ds_read_b128 v[168:171], v176 offset:1024
	ds_read_b128 v[172:175], v176 offset:2048
	ds_read_b128 v[176:179], v176 offset:3072
	s_add_u32 s46, s46, 0x80000
	s_addc_u32 s47, s47, 0
	s_mov_b32 m0, s63
	v_lshl_add_u64 v[228:229], s[46:47], 0, v[152:153]
	ds_read_b128 v[190:193], v187 offset:32768
	ds_read_b128 v[194:197], v187 offset:33792
	ds_read_b128 v[198:201], v187 offset:34816
	ds_read_b128 v[202:205], v187 offset:35840
	ds_read_b128 v[206:209], v187 offset:36864
	ds_read_b128 v[210:213], v187 offset:37888
	ds_read_b128 v[214:217], v187 offset:38912
	ds_read_b128 v[218:221], v187 offset:39936
	global_load_lds_dwordx4 v[228:229], off
	v_lshl_add_u64 v[228:229], s[46:47], 0, v[148:149]
	s_mov_b32 m0, s64
	s_nop 0
	global_load_lds_dwordx4 v[228:229], off
	s_waitcnt vmcnt(8)
	s_waitcnt lgkmcnt(0)
	s_barrier
	s_setprio 1
	s_waitcnt lgkmcnt(0)
	v_mfma_f32_16x16x32_bf16 v[126:129], v[130:133], v[190:193], v[126:129]
	v_mfma_f32_16x16x32_bf16 v[122:125], v[138:141], v[190:193], v[122:125]
	v_mfma_f32_16x16x32_bf16 v[118:121], v[130:133], v[198:201], v[118:121]
	v_mfma_f32_16x16x32_bf16 v[110:113], v[138:141], v[198:201], v[110:113]
	v_mfma_f32_16x16x32_bf16 v[102:105], v[130:133], v[206:209], v[102:105]
	v_mfma_f32_16x16x32_bf16 v[94:97], v[138:141], v[206:209], v[94:97]
	v_mfma_f32_16x16x32_bf16 v[86:89], v[130:133], v[214:217], v[86:89]
	v_mfma_f32_16x16x32_bf16 v[78:81], v[138:141], v[214:217], v[78:81]
	v_mfma_f32_16x16x32_bf16 v[126:129], v[134:137], v[194:197], v[126:129]
	v_mfma_f32_16x16x32_bf16 v[122:125], v[142:145], v[194:197], v[122:125]
	v_mfma_f32_16x16x32_bf16 v[118:121], v[134:137], v[202:205], v[118:121]
	v_mfma_f32_16x16x32_bf16 v[110:113], v[142:145], v[202:205], v[110:113]
	v_mfma_f32_16x16x32_bf16 v[102:105], v[134:137], v[210:213], v[102:105]
	v_mfma_f32_16x16x32_bf16 v[94:97], v[142:145], v[210:213], v[94:97]
	v_mfma_f32_16x16x32_bf16 v[86:89], v[134:137], v[218:221], v[86:89]
	v_mfma_f32_16x16x32_bf16 v[78:81], v[142:145], v[218:221], v[78:81]
	s_setprio 0
	s_setprio 1
	v_mfma_f32_16x16x32_bf16 v[114:117], v[164:167], v[190:193], v[114:117]
	v_mfma_f32_16x16x32_bf16 v[106:109], v[172:175], v[190:193], v[106:109]
	v_mfma_f32_16x16x32_bf16 v[98:101], v[164:167], v[198:201], v[98:101]
	v_mfma_f32_16x16x32_bf16 v[90:93], v[172:175], v[198:201], v[90:93]
	v_mfma_f32_16x16x32_bf16 v[82:85], v[164:167], v[206:209], v[82:85]
	v_mfma_f32_16x16x32_bf16 v[74:77], v[172:175], v[206:209], v[74:77]
	v_mfma_f32_16x16x32_bf16 v[70:73], v[164:167], v[214:217], v[70:73]
	v_mfma_f32_16x16x32_bf16 v[66:69], v[172:175], v[214:217], v[66:69]
	v_mfma_f32_16x16x32_bf16 v[114:117], v[168:171], v[194:197], v[114:117]
	v_mfma_f32_16x16x32_bf16 v[106:109], v[176:179], v[194:197], v[106:109]
	v_mfma_f32_16x16x32_bf16 v[98:101], v[168:171], v[202:205], v[98:101]
	v_mfma_f32_16x16x32_bf16 v[90:93], v[176:179], v[202:205], v[90:93]
	v_mfma_f32_16x16x32_bf16 v[82:85], v[168:171], v[210:213], v[82:85]
	v_mfma_f32_16x16x32_bf16 v[74:77], v[176:179], v[210:213], v[74:77]
	v_mfma_f32_16x16x32_bf16 v[70:73], v[168:171], v[218:221], v[70:73]
	v_mfma_f32_16x16x32_bf16 v[66:69], v[176:179], v[218:221], v[66:69]
	s_setprio 0
	s_barrier
	s_add_i32 s46, s82, s48
	v_lshl_add_u64 v[180:181], v[180:181], 0, s[20:21]
	s_mov_b32 m0, s46
	ds_read_b128 v[190:193], v187 offset:49152
	ds_read_b128 v[194:197], v187 offset:50176
	ds_read_b128 v[198:201], v187 offset:51200
	ds_read_b128 v[202:205], v187 offset:52224
	ds_read_b128 v[206:209], v187 offset:53248
	ds_read_b128 v[210:213], v187 offset:54272
	ds_read_b128 v[214:217], v187 offset:55296
	ds_read_b128 v[218:221], v187 offset:56320
	global_load_lds_dwordx4 v[180:181], off
	s_add_i32 m0, s46, 0x2000
	s_add_u32 s44, s44, 0x80080
	v_lshl_add_u64 v[180:181], v[222:223], 0, s[20:21]
	s_addc_u32 s45, s45, 0
	s_add_i32 s46, s83, s48
	global_load_lds_dwordx4 v[180:181], off
	v_lshl_add_u64 v[180:181], s[44:45], 0, v[150:151]
	s_mov_b32 m0, s46
	s_nop 0
	global_load_lds_dwordx4 v[180:181], off
	v_lshl_add_u64 v[180:181], s[44:45], 0, v[146:147]
	s_add_i32 m0, s46, 0x2000
	s_nop 0
	global_load_lds_dwordx4 v[180:181], off
	v_lshl_add_u64 v[180:181], v[224:225], 0, s[20:21]
	s_mov_b32 m0, s66
	s_nop 0
	global_load_lds_dwordx4 v[180:181], off
	v_lshl_add_u64 v[180:181], v[226:227], 0, s[20:21]
	s_mov_b32 m0, s67
	s_nop 0
	global_load_lds_dwordx4 v[180:181], off
	s_waitcnt vmcnt(8)
	s_waitcnt lgkmcnt(0)
	s_barrier
	s_setprio 1
	s_waitcnt lgkmcnt(0)
	v_mfma_f32_16x16x32_bf16 v[62:65], v[130:133], v[190:193], v[62:65]
	v_mfma_f32_16x16x32_bf16 v[58:61], v[138:141], v[190:193], v[58:61]
	v_mfma_f32_16x16x32_bf16 v[54:57], v[130:133], v[198:201], v[54:57]
	v_mfma_f32_16x16x32_bf16 v[46:49], v[138:141], v[198:201], v[46:49]
	v_mfma_f32_16x16x32_bf16 v[38:41], v[130:133], v[206:209], v[38:41]
	v_mfma_f32_16x16x32_bf16 v[30:33], v[138:141], v[206:209], v[30:33]
	v_mfma_f32_16x16x32_bf16 v[22:25], v[130:133], v[214:217], v[22:25]
	v_mfma_f32_16x16x32_bf16 v[14:17], v[138:141], v[214:217], v[14:17]
	v_mfma_f32_16x16x32_bf16 v[62:65], v[134:137], v[194:197], v[62:65]
	v_mfma_f32_16x16x32_bf16 v[58:61], v[142:145], v[194:197], v[58:61]
	v_mfma_f32_16x16x32_bf16 v[54:57], v[134:137], v[202:205], v[54:57]
	v_mfma_f32_16x16x32_bf16 v[46:49], v[142:145], v[202:205], v[46:49]
	v_mfma_f32_16x16x32_bf16 v[38:41], v[134:137], v[210:213], v[38:41]
	v_mfma_f32_16x16x32_bf16 v[30:33], v[142:145], v[210:213], v[30:33]
	v_mfma_f32_16x16x32_bf16 v[22:25], v[134:137], v[218:221], v[22:25]
	v_mfma_f32_16x16x32_bf16 v[14:17], v[142:145], v[218:221], v[14:17]
	s_setprio 0
	s_setprio 1
	v_mfma_f32_16x16x32_bf16 v[50:53], v[164:167], v[190:193], v[50:53]
	v_mfma_f32_16x16x32_bf16 v[42:45], v[172:175], v[190:193], v[42:45]
	v_mfma_f32_16x16x32_bf16 v[34:37], v[164:167], v[198:201], v[34:37]
	v_mfma_f32_16x16x32_bf16 v[26:29], v[172:175], v[198:201], v[26:29]
	v_mfma_f32_16x16x32_bf16 v[18:21], v[164:167], v[206:209], v[18:21]
	v_mfma_f32_16x16x32_bf16 v[10:13], v[172:175], v[206:209], v[10:13]
	v_mfma_f32_16x16x32_bf16 v[6:9], v[164:167], v[214:217], v[6:9]
	v_mfma_f32_16x16x32_bf16 v[2:5], v[172:175], v[214:217], v[2:5]
	v_mfma_f32_16x16x32_bf16 v[50:53], v[168:171], v[194:197], v[50:53]
	v_mfma_f32_16x16x32_bf16 v[42:45], v[176:179], v[194:197], v[42:45]
	v_mfma_f32_16x16x32_bf16 v[34:37], v[168:171], v[202:205], v[34:37]
	v_mfma_f32_16x16x32_bf16 v[26:29], v[176:179], v[202:205], v[26:29]
	v_mfma_f32_16x16x32_bf16 v[18:21], v[168:171], v[210:213], v[18:21]
	v_mfma_f32_16x16x32_bf16 v[10:13], v[176:179], v[210:213], v[10:13]
	v_mfma_f32_16x16x32_bf16 v[6:9], v[168:171], v[218:221], v[6:9]
	v_mfma_f32_16x16x32_bf16 v[2:5], v[176:179], v[218:221], v[2:5]
	s_setprio 0
	s_add_i32 s81, s81, 2
	s_add_u32 s10, s10, 0x100
	s_addc_u32 s11, s11, 0
	s_add_u32 s73, s73, 0x100
	s_addc_u32 s80, s80, 0
	s_cmp_gt_u32 s81, 29
	s_barrier
	s_cbranch_scc0 .LBB0_894
	s_and_b64 vcc, exec, s[22:23]
	s_cbranch_vccz .LBB0_897
	s_barrier

.LBB0_1088:
	ds_read_b128 v[144:147], v155
	ds_read_b128 v[148:151], v155 offset:1024
	ds_read_b128 v[158:161], v155 offset:2048
	ds_read_b128 v[162:165], v155 offset:3072
	ds_read_b128 v[166:169], v156
	ds_read_b128 v[170:173], v156 offset:1024
	ds_read_b128 v[174:177], v156 offset:2048
	ds_read_b128 v[178:181], v156 offset:3072
	s_add_u32 s18, s16, 0xffea0080
	s_addc_u32 s19, s17, -1
	s_cmpk_eq_i32 s43, 0x54
	s_cselect_b32 s21, s5, s19
	s_cselect_b32 s20, s4, s18
	s_cselect_b32 s19, s15, s42
	s_cselect_b32 s18, s14, s41
	v_lshl_add_u64 v[214:215], s[16:17], 0, v[136:137]
	s_add_i32 m0, s25, 0xc000
	ds_read_b128 v[182:185], v157
	ds_read_b128 v[186:189], v157 offset:1024
	ds_read_b128 v[190:193], v157 offset:2048
	ds_read_b128 v[194:197], v157 offset:3072
	ds_read_b128 v[198:201], v157 offset:4096
	ds_read_b128 v[202:205], v157 offset:5120
	ds_read_b128 v[206:209], v157 offset:6144
	ds_read_b128 v[210:213], v157 offset:7168
	global_load_lds_dwordx4 v[214:215], off
	v_lshl_add_u64 v[214:215], s[16:17], 0, v[138:139]
	s_add_i32 m0, s25, 0xe000
	s_nop 0
	global_load_lds_dwordx4 v[214:215], off
	s_waitcnt vmcnt(8)
	s_waitcnt lgkmcnt(0)
	s_barrier
	s_setprio 1
	s_waitcnt lgkmcnt(0)
	v_mfma_f32_16x16x32_bf16 v[124:127], v[144:147], v[182:185], v[124:127]
	v_mfma_f32_16x16x32_bf16 v[120:123], v[158:161], v[182:185], v[120:123]
	v_mfma_f32_16x16x32_bf16 v[112:115], v[144:147], v[190:193], v[112:115]
	v_mfma_f32_16x16x32_bf16 v[104:107], v[158:161], v[190:193], v[104:107]
	v_mfma_f32_16x16x32_bf16 v[92:95], v[144:147], v[198:201], v[92:95]
	v_mfma_f32_16x16x32_bf16 v[88:91], v[158:161], v[198:201], v[88:91]
	v_mfma_f32_16x16x32_bf16 v[80:83], v[144:147], v[206:209], v[80:83]
	v_mfma_f32_16x16x32_bf16 v[72:75], v[158:161], v[206:209], v[72:75]
	v_mfma_f32_16x16x32_bf16 v[124:127], v[148:151], v[186:189], v[124:127]
	v_mfma_f32_16x16x32_bf16 v[120:123], v[162:165], v[186:189], v[120:123]
	v_mfma_f32_16x16x32_bf16 v[112:115], v[148:151], v[194:197], v[112:115]
	v_mfma_f32_16x16x32_bf16 v[104:107], v[162:165], v[194:197], v[104:107]
	v_mfma_f32_16x16x32_bf16 v[92:95], v[148:151], v[202:205], v[92:95]
	v_mfma_f32_16x16x32_bf16 v[88:91], v[162:165], v[202:205], v[88:91]
	v_mfma_f32_16x16x32_bf16 v[80:83], v[148:151], v[210:213], v[80:83]
	v_mfma_f32_16x16x32_bf16 v[72:75], v[162:165], v[210:213], v[72:75]
	s_setprio 0
	s_setprio 1
	v_mfma_f32_16x16x32_bf16 v[116:119], v[166:169], v[182:185], v[116:119]
	v_mfma_f32_16x16x32_bf16 v[108:111], v[174:177], v[182:185], v[108:111]
	v_mfma_f32_16x16x32_bf16 v[100:103], v[166:169], v[190:193], v[100:103]
	v_mfma_f32_16x16x32_bf16 v[96:99], v[174:177], v[190:193], v[96:99]
	v_mfma_f32_16x16x32_bf16 v[84:87], v[166:169], v[198:201], v[84:87]
	v_mfma_f32_16x16x32_bf16 v[76:79], v[174:177], v[198:201], v[76:79]
	v_mfma_f32_16x16x32_bf16 v[68:71], v[166:169], v[206:209], v[68:71]
	v_mfma_f32_16x16x32_bf16 v[64:67], v[174:177], v[206:209], v[64:67]
	v_mfma_f32_16x16x32_bf16 v[116:119], v[170:173], v[186:189], v[116:119]
	v_mfma_f32_16x16x32_bf16 v[108:111], v[178:181], v[186:189], v[108:111]
	v_mfma_f32_16x16x32_bf16 v[100:103], v[170:173], v[194:197], v[100:103]
	v_mfma_f32_16x16x32_bf16 v[96:99], v[178:181], v[194:197], v[96:99]
	v_mfma_f32_16x16x32_bf16 v[84:87], v[170:173], v[202:205], v[84:87]
	v_mfma_f32_16x16x32_bf16 v[76:79], v[178:181], v[202:205], v[76:79]
	v_mfma_f32_16x16x32_bf16 v[68:71], v[170:173], v[210:213], v[68:71]
	v_mfma_f32_16x16x32_bf16 v[64:67], v[178:181], v[210:213], v[64:67]
	s_setprio 0
	s_barrier
	s_add_i32 s44, s35, s24
	v_lshl_add_u64 v[214:215], s[18:19], 0, v[130:131]
	s_mov_b32 m0, s44
	ds_read_b128 v[182:185], v157 offset:16384
	ds_read_b128 v[186:189], v157 offset:17408
	ds_read_b128 v[190:193], v157 offset:18432
	ds_read_b128 v[194:197], v157 offset:19456
	ds_read_b128 v[198:201], v157 offset:20480
	ds_read_b128 v[202:205], v157 offset:21504
	ds_read_b128 v[206:209], v157 offset:22528
	ds_read_b128 v[210:213], v157 offset:23552
	global_load_lds_dwordx4 v[214:215], off
	s_add_i32 m0, s44, 0x2000
	s_add_u32 s44, s18, 0x160000
	v_lshl_add_u64 v[216:217], s[18:19], 0, v[134:135]
	s_addc_u32 s45, s19, 0
	s_add_i32 s46, s36, s24
	global_load_lds_dwordx4 v[216:217], off
	v_lshl_add_u64 v[218:219], s[44:45], 0, v[130:131]
	s_mov_b32 m0, s46
	v_lshl_add_u64 v[220:221], s[20:21], 0, v[132:133]
	global_load_lds_dwordx4 v[218:219], off
	v_lshl_add_u64 v[218:219], s[44:45], 0, v[134:135]
	s_add_i32 m0, s46, 0x2000
	s_nop 0
	global_load_lds_dwordx4 v[218:219], off
	v_lshl_add_u64 v[218:219], s[20:21], 0, v[128:129]
	s_mov_b32 m0, s25
	s_nop 0
	global_load_lds_dwordx4 v[218:219], off
	s_mov_b32 m0, s26
	s_nop 0
	global_load_lds_dwordx4 v[220:221], off
	s_waitcnt vmcnt(8)
	s_waitcnt lgkmcnt(0)
	s_barrier
	s_setprio 1
	s_waitcnt lgkmcnt(0)
	v_mfma_f32_16x16x32_bf16 v[60:63], v[144:147], v[182:185], v[60:63]
	v_mfma_f32_16x16x32_bf16 v[56:59], v[158:161], v[182:185], v[56:59]
	v_mfma_f32_16x16x32_bf16 v[48:51], v[144:147], v[190:193], v[48:51]
	v_mfma_f32_16x16x32_bf16 v[40:43], v[158:161], v[190:193], v[40:43]
	v_mfma_f32_16x16x32_bf16 v[28:31], v[144:147], v[198:201], v[28:31]
	v_mfma_f32_16x16x32_bf16 v[24:27], v[158:161], v[198:201], v[24:27]
	v_mfma_f32_16x16x32_bf16 v[20:23], v[144:147], v[206:209], v[20:23]
	v_mfma_f32_16x16x32_bf16 v[12:15], v[158:161], v[206:209], v[12:15]
	v_mfma_f32_16x16x32_bf16 v[60:63], v[148:151], v[186:189], v[60:63]
	v_mfma_f32_16x16x32_bf16 v[56:59], v[162:165], v[186:189], v[56:59]
	v_mfma_f32_16x16x32_bf16 v[48:51], v[148:151], v[194:197], v[48:51]
	v_mfma_f32_16x16x32_bf16 v[40:43], v[162:165], v[194:197], v[40:43]
	v_mfma_f32_16x16x32_bf16 v[28:31], v[148:151], v[202:205], v[28:31]
	v_mfma_f32_16x16x32_bf16 v[24:27], v[162:165], v[202:205], v[24:27]
	v_mfma_f32_16x16x32_bf16 v[20:23], v[148:151], v[210:213], v[20:23]
	v_mfma_f32_16x16x32_bf16 v[12:15], v[162:165], v[210:213], v[12:15]
	s_setprio 0
	s_setprio 1
	v_mfma_f32_16x16x32_bf16 v[52:55], v[166:169], v[182:185], v[52:55]
	v_mfma_f32_16x16x32_bf16 v[44:47], v[174:177], v[182:185], v[44:47]
	v_mfma_f32_16x16x32_bf16 v[36:39], v[166:169], v[190:193], v[36:39]
	v_mfma_f32_16x16x32_bf16 v[32:35], v[174:177], v[190:193], v[32:35]
	v_mfma_f32_16x16x32_bf16 v[16:19], v[166:169], v[198:201], v[16:19]
	v_mfma_f32_16x16x32_bf16 v[8:11], v[174:177], v[198:201], v[8:11]
	v_mfma_f32_16x16x32_bf16 v[4:7], v[166:169], v[206:209], v[4:7]
	v_mfma_f32_16x16x32_bf16 v[0:3], v[174:177], v[206:209], v[0:3]
	v_mfma_f32_16x16x32_bf16 v[52:55], v[170:173], v[186:189], v[52:55]
	v_mfma_f32_16x16x32_bf16 v[44:47], v[178:181], v[186:189], v[44:47]
	v_mfma_f32_16x16x32_bf16 v[36:39], v[170:173], v[194:197], v[36:39]
	v_mfma_f32_16x16x32_bf16 v[32:35], v[178:181], v[194:197], v[32:35]
	v_mfma_f32_16x16x32_bf16 v[16:19], v[170:173], v[202:205], v[16:19]
	v_mfma_f32_16x16x32_bf16 v[8:11], v[178:181], v[202:205], v[8:11]
	v_mfma_f32_16x16x32_bf16 v[4:7], v[170:173], v[210:213], v[4:7]
	v_mfma_f32_16x16x32_bf16 v[0:3], v[178:181], v[210:213], v[0:3]
	s_setprio 0
	s_barrier
	s_add_i32 s44, 0, 0x18000
	s_add_i32 s45, 0, 0x1c000
	v_add_u32_e32 v162, s44, v153
	v_add_u32_e32 v178, s45, v153
	ds_read_b128 v[144:147], v162
	ds_read_b128 v[148:151], v162 offset:1024
	ds_read_b128 v[158:161], v162 offset:2048
	ds_read_b128 v[162:165], v162 offset:3072
	ds_read_b128 v[166:169], v178
	ds_read_b128 v[170:173], v178 offset:1024
	ds_read_b128 v[174:177], v178 offset:2048
	ds_read_b128 v[178:181], v178 offset:3072
	s_add_u32 s20, s20, 0x160000
	s_addc_u32 s21, s21, 0
	s_mov_b32 m0, s27
	v_lshl_add_u64 v[222:223], s[20:21], 0, v[128:129]
	ds_read_b128 v[182:185], v157 offset:32768
	ds_read_b128 v[186:189], v157 offset:33792
	ds_read_b128 v[190:193], v157 offset:34816
	ds_read_b128 v[194:197], v157 offset:35840
	ds_read_b128 v[198:201], v157 offset:36864
	ds_read_b128 v[202:205], v157 offset:37888
	ds_read_b128 v[206:209], v157 offset:38912
	ds_read_b128 v[210:213], v157 offset:39936
	global_load_lds_dwordx4 v[222:223], off
	v_lshl_add_u64 v[222:223], s[20:21], 0, v[132:133]
	s_mov_b32 m0, s28
	s_nop 0
	global_load_lds_dwordx4 v[222:223], off
	s_waitcnt vmcnt(8)
	s_waitcnt lgkmcnt(0)
	s_barrier
	s_setprio 1
	s_waitcnt lgkmcnt(0)
	v_mfma_f32_16x16x32_bf16 v[124:127], v[144:147], v[182:185], v[124:127]
	v_mfma_f32_16x16x32_bf16 v[120:123], v[158:161], v[182:185], v[120:123]
	v_mfma_f32_16x16x32_bf16 v[112:115], v[144:147], v[190:193], v[112:115]
	v_mfma_f32_16x16x32_bf16 v[104:107], v[158:161], v[190:193], v[104:107]
	v_mfma_f32_16x16x32_bf16 v[92:95], v[144:147], v[198:201], v[92:95]
	v_mfma_f32_16x16x32_bf16 v[88:91], v[158:161], v[198:201], v[88:91]
	v_mfma_f32_16x16x32_bf16 v[80:83], v[144:147], v[206:209], v[80:83]
	v_mfma_f32_16x16x32_bf16 v[72:75], v[158:161], v[206:209], v[72:75]
	v_mfma_f32_16x16x32_bf16 v[124:127], v[148:151], v[186:189], v[124:127]
	v_mfma_f32_16x16x32_bf16 v[120:123], v[162:165], v[186:189], v[120:123]
	v_mfma_f32_16x16x32_bf16 v[112:115], v[148:151], v[194:197], v[112:115]
	v_mfma_f32_16x16x32_bf16 v[104:107], v[162:165], v[194:197], v[104:107]
	v_mfma_f32_16x16x32_bf16 v[92:95], v[148:151], v[202:205], v[92:95]
	v_mfma_f32_16x16x32_bf16 v[88:91], v[162:165], v[202:205], v[88:91]
	v_mfma_f32_16x16x32_bf16 v[80:83], v[148:151], v[210:213], v[80:83]
	v_mfma_f32_16x16x32_bf16 v[72:75], v[162:165], v[210:213], v[72:75]
	s_setprio 0
	s_setprio 1
	v_mfma_f32_16x16x32_bf16 v[116:119], v[166:169], v[182:185], v[116:119]
	v_mfma_f32_16x16x32_bf16 v[108:111], v[174:177], v[182:185], v[108:111]
	v_mfma_f32_16x16x32_bf16 v[100:103], v[166:169], v[190:193], v[100:103]
	v_mfma_f32_16x16x32_bf16 v[96:99], v[174:177], v[190:193], v[96:99]
	v_mfma_f32_16x16x32_bf16 v[84:87], v[166:169], v[198:201], v[84:87]
	v_mfma_f32_16x16x32_bf16 v[76:79], v[174:177], v[198:201], v[76:79]
	v_mfma_f32_16x16x32_bf16 v[68:71], v[166:169], v[206:209], v[68:71]
	v_mfma_f32_16x16x32_bf16 v[64:67], v[174:177], v[206:209], v[64:67]
	v_mfma_f32_16x16x32_bf16 v[116:119], v[170:173], v[186:189], v[116:119]
	v_mfma_f32_16x16x32_bf16 v[108:111], v[178:181], v[186:189], v[108:111]
	v_mfma_f32_16x16x32_bf16 v[100:103], v[170:173], v[194:197], v[100:103]
	v_mfma_f32_16x16x32_bf16 v[96:99], v[178:181], v[194:197], v[96:99]
	v_mfma_f32_16x16x32_bf16 v[84:87], v[170:173], v[202:205], v[84:87]
	v_mfma_f32_16x16x32_bf16 v[76:79], v[178:181], v[202:205], v[76:79]
	v_mfma_f32_16x16x32_bf16 v[68:71], v[170:173], v[210:213], v[68:71]
	v_mfma_f32_16x16x32_bf16 v[64:67], v[178:181], v[210:213], v[64:67]
	s_setprio 0
	s_barrier
	s_add_i32 s20, s44, s24
	v_lshl_add_u64 v[214:215], v[214:215], 0, s[10:11]
	s_mov_b32 m0, s20
	ds_read_b128 v[182:185], v157 offset:49152
	ds_read_b128 v[186:189], v157 offset:50176
	ds_read_b128 v[190:193], v157 offset:51200
	ds_read_b128 v[194:197], v157 offset:52224
	ds_read_b128 v[198:201], v157 offset:53248
	ds_read_b128 v[202:205], v157 offset:54272
	ds_read_b128 v[206:209], v157 offset:55296
	ds_read_b128 v[210:213], v157 offset:56320
	global_load_lds_dwordx4 v[214:215], off
	s_add_i32 m0, s20, 0x2000
	s_add_u32 s18, s18, 0x160080
	v_lshl_add_u64 v[214:215], v[216:217], 0, s[10:11]
	s_addc_u32 s19, s19, 0
	s_add_i32 s20, s45, s24
	global_load_lds_dwordx4 v[214:215], off
	v_lshl_add_u64 v[214:215], s[18:19], 0, v[130:131]
	s_mov_b32 m0, s20
	s_nop 0
	global_load_lds_dwordx4 v[214:215], off
	v_lshl_add_u64 v[214:215], s[18:19], 0, v[134:135]
	s_add_i32 m0, s20, 0x2000
	s_nop 0
	global_load_lds_dwordx4 v[214:215], off
	v_lshl_add_u64 v[214:215], v[218:219], 0, s[10:11]
	s_mov_b32 m0, s31
	s_nop 0
	global_load_lds_dwordx4 v[214:215], off
	v_lshl_add_u64 v[214:215], v[220:221], 0, s[10:11]
	s_mov_b32 m0, s33
	s_nop 0
	global_load_lds_dwordx4 v[214:215], off
	s_waitcnt vmcnt(8)
	s_waitcnt lgkmcnt(0)
	s_barrier
	s_setprio 1
	s_waitcnt lgkmcnt(0)
	v_mfma_f32_16x16x32_bf16 v[60:63], v[144:147], v[182:185], v[60:63]
	v_mfma_f32_16x16x32_bf16 v[56:59], v[158:161], v[182:185], v[56:59]
	v_mfma_f32_16x16x32_bf16 v[48:51], v[144:147], v[190:193], v[48:51]
	v_mfma_f32_16x16x32_bf16 v[40:43], v[158:161], v[190:193], v[40:43]
	v_mfma_f32_16x16x32_bf16 v[28:31], v[144:147], v[198:201], v[28:31]
	v_mfma_f32_16x16x32_bf16 v[24:27], v[158:161], v[198:201], v[24:27]
	v_mfma_f32_16x16x32_bf16 v[20:23], v[144:147], v[206:209], v[20:23]
	v_mfma_f32_16x16x32_bf16 v[12:15], v[158:161], v[206:209], v[12:15]
	v_mfma_f32_16x16x32_bf16 v[60:63], v[148:151], v[186:189], v[60:63]
	v_mfma_f32_16x16x32_bf16 v[56:59], v[162:165], v[186:189], v[56:59]
	v_mfma_f32_16x16x32_bf16 v[48:51], v[148:151], v[194:197], v[48:51]
	v_mfma_f32_16x16x32_bf16 v[40:43], v[162:165], v[194:197], v[40:43]
	v_mfma_f32_16x16x32_bf16 v[28:31], v[148:151], v[202:205], v[28:31]
	v_mfma_f32_16x16x32_bf16 v[24:27], v[162:165], v[202:205], v[24:27]
	v_mfma_f32_16x16x32_bf16 v[20:23], v[148:151], v[210:213], v[20:23]
	v_mfma_f32_16x16x32_bf16 v[12:15], v[162:165], v[210:213], v[12:15]
	s_setprio 0
	s_setprio 1
	v_mfma_f32_16x16x32_bf16 v[52:55], v[166:169], v[182:185], v[52:55]
	v_mfma_f32_16x16x32_bf16 v[44:47], v[174:177], v[182:185], v[44:47]
	v_mfma_f32_16x16x32_bf16 v[36:39], v[166:169], v[190:193], v[36:39]
	v_mfma_f32_16x16x32_bf16 v[32:35], v[174:177], v[190:193], v[32:35]
	v_mfma_f32_16x16x32_bf16 v[16:19], v[166:169], v[198:201], v[16:19]
	v_mfma_f32_16x16x32_bf16 v[8:11], v[174:177], v[198:201], v[8:11]
	v_mfma_f32_16x16x32_bf16 v[4:7], v[166:169], v[206:209], v[4:7]
	v_mfma_f32_16x16x32_bf16 v[0:3], v[174:177], v[206:209], v[0:3]
	v_mfma_f32_16x16x32_bf16 v[52:55], v[170:173], v[186:189], v[52:55]
	v_mfma_f32_16x16x32_bf16 v[44:47], v[178:181], v[186:189], v[44:47]
	v_mfma_f32_16x16x32_bf16 v[36:39], v[170:173], v[194:197], v[36:39]
	v_mfma_f32_16x16x32_bf16 v[32:35], v[178:181], v[194:197], v[32:35]
	v_mfma_f32_16x16x32_bf16 v[16:19], v[170:173], v[202:205], v[16:19]
	v_mfma_f32_16x16x32_bf16 v[8:11], v[178:181], v[202:205], v[8:11]
	v_mfma_f32_16x16x32_bf16 v[4:7], v[170:173], v[210:213], v[4:7]
	v_mfma_f32_16x16x32_bf16 v[0:3], v[178:181], v[210:213], v[0:3]
	s_setprio 0
	s_add_i32 s43, s43, 2
	s_add_u32 s16, s16, 0x100
	s_addc_u32 s17, s17, 0
	s_add_u32 s41, s41, 0x100
	s_addc_u32 s42, s42, 0
	s_cmpk_gt_u32 s43, 0x55
	s_barrier
	s_cbranch_scc0 .LBB0_1088
	s_and_b64 vcc, exec, s[12:13]
	s_cbranch_vccz .LBB0_1091
	s_barrier
